# GEMM K-loops: snake MFMA order - accumulator k-steps adjacent and consecutive MFMAs share one operand register (k order alternates per chain; same bf16 MFMA / f32 accumulate precision)
# speedup vs baseline: 1.0127x; 1.0036x over previous
.LBB0_261:
	s_add_u32 s0, s76, 0xfff80080
	s_addc_u32 s1, s77, -1
	s_and_b64 s[84:85], s[84:85], exec
	s_cselect_b32 vcc_hi, s22, s1
	s_cselect_b32 vcc_lo, s23, s0
	s_cselect_b32 s85, s49, s58
	s_cselect_b32 s84, s57, s51
	s_add_i32 s0, 0, 0x10000
	s_add_i32 s1, 0, 0x14000
	v_add_u32_e32 v158, s0, v176
	v_add_u32_e32 v174, s1, v176
	ds_read_b128 v[146:149], v158
	ds_read_b128 v[150:153], v158 offset:1024
	ds_read_b128 v[154:157], v158 offset:2048
	ds_read_b128 v[158:161], v158 offset:3072
	ds_read_b128 v[162:165], v174
	ds_read_b128 v[166:169], v174 offset:1024
	ds_read_b128 v[170:173], v174 offset:2048
	ds_read_b128 v[178:181], v174 offset:3072
	v_lshl_add_u64 v[174:175], s[76:77], 0, v[138:139]
	s_add_i32 m0, s21, 0xc000
	ds_read_b128 v[182:185], v177
	ds_read_b128 v[186:189], v177 offset:1024
	ds_read_b128 v[190:193], v177 offset:2048
	ds_read_b128 v[204:207], v177 offset:3072
	ds_read_b128 v[208:211], v177 offset:4096
	ds_read_b128 v[212:215], v177 offset:5120
	ds_read_b128 v[216:219], v177 offset:6144
	ds_read_b128 v[220:223], v177 offset:7168
	global_load_lds_dwordx4 v[174:175], off
	v_lshl_add_u64 v[174:175], s[76:77], 0, v[140:141]
	s_add_i32 m0, s21, 0xe000
	s_nop 0
	global_load_lds_dwordx4 v[174:175], off
	s_waitcnt vmcnt(8)
	s_waitcnt lgkmcnt(0)
	s_barrier
	s_setprio 1
	s_waitcnt lgkmcnt(0)
	v_mfma_f32_16x16x32_bf16 v[126:129], v[146:149], v[182:185], v[126:129]
	v_mfma_f32_16x16x32_bf16 v[126:129], v[150:153], v[186:189], v[126:129]
	v_mfma_f32_16x16x32_bf16 v[122:125], v[158:161], v[186:189], v[122:125]
	v_mfma_f32_16x16x32_bf16 v[122:125], v[154:157], v[182:185], v[122:125]
	v_mfma_f32_16x16x32_bf16 v[106:109], v[154:157], v[190:193], v[106:109]
	v_mfma_f32_16x16x32_bf16 v[106:109], v[158:161], v[204:207], v[106:109]
	v_mfma_f32_16x16x32_bf16 v[110:113], v[150:153], v[204:207], v[110:113]
	v_mfma_f32_16x16x32_bf16 v[110:113], v[146:149], v[190:193], v[110:113]
	v_mfma_f32_16x16x32_bf16 v[94:97], v[146:149], v[208:211], v[94:97]
	v_mfma_f32_16x16x32_bf16 v[94:97], v[150:153], v[212:215], v[94:97]
	v_mfma_f32_16x16x32_bf16 v[90:93], v[158:161], v[212:215], v[90:93]
	v_mfma_f32_16x16x32_bf16 v[90:93], v[154:157], v[208:211], v[90:93]
	v_mfma_f32_16x16x32_bf16 v[74:77], v[154:157], v[216:219], v[74:77]
	v_mfma_f32_16x16x32_bf16 v[74:77], v[158:161], v[220:223], v[74:77]
	v_mfma_f32_16x16x32_bf16 v[78:81], v[150:153], v[220:223], v[78:81]
	v_mfma_f32_16x16x32_bf16 v[78:81], v[146:149], v[216:219], v[78:81]
	s_setprio 0
	s_setprio 1
	v_mfma_f32_16x16x32_bf16 v[118:121], v[162:165], v[182:185], v[118:121]
	v_mfma_f32_16x16x32_bf16 v[118:121], v[166:169], v[186:189], v[118:121]
	v_mfma_f32_16x16x32_bf16 v[114:117], v[178:181], v[186:189], v[114:117]
	v_mfma_f32_16x16x32_bf16 v[114:117], v[170:173], v[182:185], v[114:117]
	v_mfma_f32_16x16x32_bf16 v[98:101], v[170:173], v[190:193], v[98:101]
	v_mfma_f32_16x16x32_bf16 v[98:101], v[178:181], v[204:207], v[98:101]
	v_mfma_f32_16x16x32_bf16 v[102:105], v[166:169], v[204:207], v[102:105]
	v_mfma_f32_16x16x32_bf16 v[102:105], v[162:165], v[190:193], v[102:105]
	v_mfma_f32_16x16x32_bf16 v[86:89], v[162:165], v[208:211], v[86:89]
	v_mfma_f32_16x16x32_bf16 v[86:89], v[166:169], v[212:215], v[86:89]
	v_mfma_f32_16x16x32_bf16 v[82:85], v[178:181], v[212:215], v[82:85]
	v_mfma_f32_16x16x32_bf16 v[82:85], v[170:173], v[208:211], v[82:85]
	v_mfma_f32_16x16x32_bf16 v[66:69], v[170:173], v[216:219], v[66:69]
	v_mfma_f32_16x16x32_bf16 v[66:69], v[178:181], v[220:223], v[66:69]
	v_mfma_f32_16x16x32_bf16 v[70:73], v[166:169], v[220:223], v[70:73]
	v_mfma_f32_16x16x32_bf16 v[70:73], v[162:165], v[216:219], v[70:73]
	s_setprio 0
	s_barrier
	s_add_i32 s0, s0, s20
	v_lshl_add_u64 v[174:175], s[84:85], 0, v[132:133]
	s_mov_b32 m0, s0
	ds_read_b128 v[182:185], v177 offset:16384
	ds_read_b128 v[186:189], v177 offset:17408
	ds_read_b128 v[190:193], v177 offset:18432
	ds_read_b128 v[204:207], v177 offset:19456
	ds_read_b128 v[208:211], v177 offset:20480
	ds_read_b128 v[212:215], v177 offset:21504
	ds_read_b128 v[216:219], v177 offset:22528
	ds_read_b128 v[220:223], v177 offset:23552
	global_load_lds_dwordx4 v[174:175], off
	s_add_i32 m0, s0, 0x2000
	s_add_u32 s94, s84, 0x80000
	v_lshl_add_u64 v[224:225], s[84:85], 0, v[130:131]
	s_addc_u32 s95, s85, 0
	s_add_i32 s0, s1, s20
	global_load_lds_dwordx4 v[224:225], off
	v_lshl_add_u64 v[226:227], s[94:95], 0, v[132:133]
	s_mov_b32 m0, s0
	v_lshl_add_u64 v[228:229], vcc, 0, v[130:131]
	global_load_lds_dwordx4 v[226:227], off
	v_lshl_add_u64 v[226:227], s[94:95], 0, v[130:131]
	s_add_i32 m0, s0, 0x2000
	s_nop 0
	global_load_lds_dwordx4 v[226:227], off
	v_lshl_add_u64 v[226:227], vcc, 0, v[132:133]
	s_mov_b32 m0, s21
	s_nop 0
	global_load_lds_dwordx4 v[226:227], off
	s_mov_b32 m0, s26
	s_nop 0
	global_load_lds_dwordx4 v[228:229], off
	s_waitcnt vmcnt(8)
	s_waitcnt lgkmcnt(0)
	s_barrier
	s_setprio 1
	s_waitcnt lgkmcnt(0)
	v_mfma_f32_16x16x32_bf16 v[62:65], v[146:149], v[182:185], v[62:65]
	v_mfma_f32_16x16x32_bf16 v[62:65], v[150:153], v[186:189], v[62:65]
	v_mfma_f32_16x16x32_bf16 v[58:61], v[158:161], v[186:189], v[58:61]
	v_mfma_f32_16x16x32_bf16 v[58:61], v[154:157], v[182:185], v[58:61]
	v_mfma_f32_16x16x32_bf16 v[42:45], v[154:157], v[190:193], v[42:45]
	v_mfma_f32_16x16x32_bf16 v[42:45], v[158:161], v[204:207], v[42:45]
	v_mfma_f32_16x16x32_bf16 v[46:49], v[150:153], v[204:207], v[46:49]
	v_mfma_f32_16x16x32_bf16 v[46:49], v[146:149], v[190:193], v[46:49]
	v_mfma_f32_16x16x32_bf16 v[30:33], v[146:149], v[208:211], v[30:33]
	v_mfma_f32_16x16x32_bf16 v[30:33], v[150:153], v[212:215], v[30:33]
	v_mfma_f32_16x16x32_bf16 v[26:29], v[158:161], v[212:215], v[26:29]
	v_mfma_f32_16x16x32_bf16 v[26:29], v[154:157], v[208:211], v[26:29]
	v_mfma_f32_16x16x32_bf16 v[10:13], v[154:157], v[216:219], v[10:13]
	v_mfma_f32_16x16x32_bf16 v[10:13], v[158:161], v[220:223], v[10:13]
	v_mfma_f32_16x16x32_bf16 v[14:17], v[150:153], v[220:223], v[14:17]
	v_mfma_f32_16x16x32_bf16 v[14:17], v[146:149], v[216:219], v[14:17]
	s_setprio 0
	s_setprio 1
	v_mfma_f32_16x16x32_bf16 v[54:57], v[162:165], v[182:185], v[54:57]
	v_mfma_f32_16x16x32_bf16 v[54:57], v[166:169], v[186:189], v[54:57]
	v_mfma_f32_16x16x32_bf16 v[50:53], v[178:181], v[186:189], v[50:53]
	v_mfma_f32_16x16x32_bf16 v[50:53], v[170:173], v[182:185], v[50:53]
	v_mfma_f32_16x16x32_bf16 v[34:37], v[170:173], v[190:193], v[34:37]
	v_mfma_f32_16x16x32_bf16 v[34:37], v[178:181], v[204:207], v[34:37]
	v_mfma_f32_16x16x32_bf16 v[38:41], v[166:169], v[204:207], v[38:41]
	v_mfma_f32_16x16x32_bf16 v[38:41], v[162:165], v[190:193], v[38:41]
	v_mfma_f32_16x16x32_bf16 v[22:25], v[162:165], v[208:211], v[22:25]
	v_mfma_f32_16x16x32_bf16 v[22:25], v[166:169], v[212:215], v[22:25]
	v_mfma_f32_16x16x32_bf16 v[18:21], v[178:181], v[212:215], v[18:21]
	v_mfma_f32_16x16x32_bf16 v[18:21], v[170:173], v[208:211], v[18:21]
	v_mfma_f32_16x16x32_bf16 v[2:5], v[170:173], v[216:219], v[2:5]
	v_mfma_f32_16x16x32_bf16 v[2:5], v[178:181], v[220:223], v[2:5]
	v_mfma_f32_16x16x32_bf16 v[6:9], v[166:169], v[220:223], v[6:9]
	v_mfma_f32_16x16x32_bf16 v[6:9], v[162:165], v[216:219], v[6:9]
	s_setprio 0
	s_barrier
	s_add_i32 s0, 0, 0x18000
	s_add_i32 s1, 0, 0x1c000
	v_add_u32_e32 v158, s0, v176
	v_add_u32_e32 v178, s1, v176
	ds_read_b128 v[146:149], v158
	ds_read_b128 v[150:153], v158 offset:1024
	ds_read_b128 v[154:157], v158 offset:2048
	ds_read_b128 v[158:161], v158 offset:3072
	ds_read_b128 v[162:165], v178
	ds_read_b128 v[166:169], v178 offset:1024
	ds_read_b128 v[170:173], v178 offset:2048
	ds_read_b128 v[178:181], v178 offset:3072
	s_add_u32 s94, vcc_lo, 0x80000
	s_addc_u32 s95, vcc_hi, 0
	s_mov_b32 m0, s27
	v_lshl_add_u64 v[230:231], s[94:95], 0, v[132:133]
	ds_read_b128 v[182:185], v177 offset:32768
	ds_read_b128 v[186:189], v177 offset:33792
	ds_read_b128 v[190:193], v177 offset:34816
	ds_read_b128 v[204:207], v177 offset:35840
	ds_read_b128 v[208:211], v177 offset:36864
	ds_read_b128 v[212:215], v177 offset:37888
	ds_read_b128 v[216:219], v177 offset:38912
	ds_read_b128 v[220:223], v177 offset:39936
	global_load_lds_dwordx4 v[230:231], off
	v_lshl_add_u64 v[230:231], s[94:95], 0, v[130:131]
	s_mov_b32 m0, s29
	s_nop 0
	global_load_lds_dwordx4 v[230:231], off
	s_waitcnt vmcnt(8)
	s_waitcnt lgkmcnt(0)
	s_barrier
	s_setprio 1
	s_waitcnt lgkmcnt(0)
	v_mfma_f32_16x16x32_bf16 v[126:129], v[146:149], v[182:185], v[126:129]
	v_mfma_f32_16x16x32_bf16 v[126:129], v[150:153], v[186:189], v[126:129]
	v_mfma_f32_16x16x32_bf16 v[122:125], v[158:161], v[186:189], v[122:125]
	v_mfma_f32_16x16x32_bf16 v[122:125], v[154:157], v[182:185], v[122:125]
	v_mfma_f32_16x16x32_bf16 v[106:109], v[154:157], v[190:193], v[106:109]
	v_mfma_f32_16x16x32_bf16 v[106:109], v[158:161], v[204:207], v[106:109]
	v_mfma_f32_16x16x32_bf16 v[110:113], v[150:153], v[204:207], v[110:113]
	v_mfma_f32_16x16x32_bf16 v[110:113], v[146:149], v[190:193], v[110:113]
	v_mfma_f32_16x16x32_bf16 v[94:97], v[146:149], v[208:211], v[94:97]
	v_mfma_f32_16x16x32_bf16 v[94:97], v[150:153], v[212:215], v[94:97]
	v_mfma_f32_16x16x32_bf16 v[90:93], v[158:161], v[212:215], v[90:93]
	v_mfma_f32_16x16x32_bf16 v[90:93], v[154:157], v[208:211], v[90:93]
	v_mfma_f32_16x16x32_bf16 v[74:77], v[154:157], v[216:219], v[74:77]
	v_mfma_f32_16x16x32_bf16 v[74:77], v[158:161], v[220:223], v[74:77]
	v_mfma_f32_16x16x32_bf16 v[78:81], v[150:153], v[220:223], v[78:81]
	v_mfma_f32_16x16x32_bf16 v[78:81], v[146:149], v[216:219], v[78:81]
	s_setprio 0
	s_setprio 1
	v_mfma_f32_16x16x32_bf16 v[118:121], v[162:165], v[182:185], v[118:121]
	v_mfma_f32_16x16x32_bf16 v[118:121], v[166:169], v[186:189], v[118:121]
	v_mfma_f32_16x16x32_bf16 v[114:117], v[178:181], v[186:189], v[114:117]
	v_mfma_f32_16x16x32_bf16 v[114:117], v[170:173], v[182:185], v[114:117]
	v_mfma_f32_16x16x32_bf16 v[98:101], v[170:173], v[190:193], v[98:101]
	v_mfma_f32_16x16x32_bf16 v[98:101], v[178:181], v[204:207], v[98:101]
	v_mfma_f32_16x16x32_bf16 v[102:105], v[166:169], v[204:207], v[102:105]
	v_mfma_f32_16x16x32_bf16 v[102:105], v[162:165], v[190:193], v[102:105]
	v_mfma_f32_16x16x32_bf16 v[86:89], v[162:165], v[208:211], v[86:89]
	v_mfma_f32_16x16x32_bf16 v[86:89], v[166:169], v[212:215], v[86:89]
	v_mfma_f32_16x16x32_bf16 v[82:85], v[178:181], v[212:215], v[82:85]
	v_mfma_f32_16x16x32_bf16 v[82:85], v[170:173], v[208:211], v[82:85]
	v_mfma_f32_16x16x32_bf16 v[66:69], v[170:173], v[216:219], v[66:69]
	v_mfma_f32_16x16x32_bf16 v[66:69], v[178:181], v[220:223], v[66:69]
	v_mfma_f32_16x16x32_bf16 v[70:73], v[166:169], v[220:223], v[70:73]
	v_mfma_f32_16x16x32_bf16 v[70:73], v[162:165], v[216:219], v[70:73]
	s_setprio 0
	s_barrier
	s_add_i32 s0, s0, s20
	v_lshl_add_u64 v[174:175], v[174:175], 0, s[82:83]
	s_mov_b32 m0, s0
	ds_read_b128 v[182:185], v177 offset:49152
	ds_read_b128 v[186:189], v177 offset:50176
	ds_read_b128 v[190:193], v177 offset:51200
	ds_read_b128 v[204:207], v177 offset:52224
	ds_read_b128 v[208:211], v177 offset:53248
	ds_read_b128 v[212:215], v177 offset:54272
	ds_read_b128 v[216:219], v177 offset:55296
	ds_read_b128 v[220:223], v177 offset:56320
	global_load_lds_dwordx4 v[174:175], off
	s_add_i32 m0, s0, 0x2000
	s_add_u32 s84, s84, 0x80080
	v_lshl_add_u64 v[174:175], v[224:225], 0, s[82:83]
	s_addc_u32 s85, s85, 0
	s_add_i32 s0, s1, s20
	global_load_lds_dwordx4 v[174:175], off
	v_lshl_add_u64 v[174:175], s[84:85], 0, v[132:133]
	s_mov_b32 m0, s0
	s_nop 0
	global_load_lds_dwordx4 v[174:175], off
	v_lshl_add_u64 v[174:175], s[84:85], 0, v[130:131]
	s_add_i32 m0, s0, 0x2000
	s_nop 0
	global_load_lds_dwordx4 v[174:175], off
	v_lshl_add_u64 v[174:175], v[226:227], 0, s[82:83]
	s_mov_b32 m0, s40
	s_nop 0
	global_load_lds_dwordx4 v[174:175], off
	v_lshl_add_u64 v[174:175], v[228:229], 0, s[82:83]
	s_mov_b32 m0, s41
	s_nop 0
	global_load_lds_dwordx4 v[174:175], off
	s_waitcnt vmcnt(8)
	s_waitcnt lgkmcnt(0)
	s_barrier
	s_setprio 1
	s_waitcnt lgkmcnt(0)
	v_mfma_f32_16x16x32_bf16 v[62:65], v[146:149], v[182:185], v[62:65]
	v_mfma_f32_16x16x32_bf16 v[62:65], v[150:153], v[186:189], v[62:65]
	v_mfma_f32_16x16x32_bf16 v[58:61], v[158:161], v[186:189], v[58:61]
	v_mfma_f32_16x16x32_bf16 v[58:61], v[154:157], v[182:185], v[58:61]
	v_mfma_f32_16x16x32_bf16 v[42:45], v[154:157], v[190:193], v[42:45]
	v_mfma_f32_16x16x32_bf16 v[42:45], v[158:161], v[204:207], v[42:45]
	v_mfma_f32_16x16x32_bf16 v[46:49], v[150:153], v[204:207], v[46:49]
	v_mfma_f32_16x16x32_bf16 v[46:49], v[146:149], v[190:193], v[46:49]
	v_mfma_f32_16x16x32_bf16 v[30:33], v[146:149], v[208:211], v[30:33]
	v_mfma_f32_16x16x32_bf16 v[30:33], v[150:153], v[212:215], v[30:33]
	v_mfma_f32_16x16x32_bf16 v[26:29], v[158:161], v[212:215], v[26:29]
	v_mfma_f32_16x16x32_bf16 v[26:29], v[154:157], v[208:211], v[26:29]
	v_mfma_f32_16x16x32_bf16 v[10:13], v[154:157], v[216:219], v[10:13]
	v_mfma_f32_16x16x32_bf16 v[10:13], v[158:161], v[220:223], v[10:13]
	v_mfma_f32_16x16x32_bf16 v[14:17], v[150:153], v[220:223], v[14:17]
	v_mfma_f32_16x16x32_bf16 v[14:17], v[146:149], v[216:219], v[14:17]
	s_setprio 0
	s_setprio 1
	v_mfma_f32_16x16x32_bf16 v[54:57], v[162:165], v[182:185], v[54:57]
	v_mfma_f32_16x16x32_bf16 v[54:57], v[166:169], v[186:189], v[54:57]
	v_mfma_f32_16x16x32_bf16 v[50:53], v[178:181], v[186:189], v[50:53]
	v_mfma_f32_16x16x32_bf16 v[50:53], v[170:173], v[182:185], v[50:53]
	v_mfma_f32_16x16x32_bf16 v[34:37], v[170:173], v[190:193], v[34:37]
	v_mfma_f32_16x16x32_bf16 v[34:37], v[178:181], v[204:207], v[34:37]
	v_mfma_f32_16x16x32_bf16 v[38:41], v[166:169], v[204:207], v[38:41]
	v_mfma_f32_16x16x32_bf16 v[38:41], v[162:165], v[190:193], v[38:41]
	v_mfma_f32_16x16x32_bf16 v[22:25], v[162:165], v[208:211], v[22:25]
	v_mfma_f32_16x16x32_bf16 v[22:25], v[166:169], v[212:215], v[22:25]
	v_mfma_f32_16x16x32_bf16 v[18:21], v[178:181], v[212:215], v[18:21]
	v_mfma_f32_16x16x32_bf16 v[18:21], v[170:173], v[208:211], v[18:21]
	v_mfma_f32_16x16x32_bf16 v[2:5], v[170:173], v[216:219], v[2:5]
	v_mfma_f32_16x16x32_bf16 v[2:5], v[178:181], v[220:223], v[2:5]
	v_mfma_f32_16x16x32_bf16 v[6:9], v[166:169], v[220:223], v[6:9]
	v_mfma_f32_16x16x32_bf16 v[6:9], v[162:165], v[216:219], v[6:9]
	s_setprio 0
	s_barrier
	s_add_i32 s65, s65, 2
	s_add_u32 s76, s76, 0x100
	s_addc_u32 s77, s77, 0
	s_add_u32 s51, s51, 0x100
	s_addc_u32 s58, s58, 0
	s_cmp_gt_u32 s65, 29
	s_cbranch_scc1 .LBB0_264

.LBB0_285:
	s_add_u32 s0, s76, 0xfff80080
	s_addc_u32 s1, s77, -1
	s_and_b64 s[70:71], s[70:71], exec
	s_cselect_b32 vcc_hi, s21, s1
	s_cselect_b32 vcc_lo, s22, s0
	s_cselect_b32 s71, s23, s41
	s_cselect_b32 s70, s39, s7
	s_add_i32 s0, 0, 0x10000
	s_add_i32 s1, 0, 0x14000
	v_add_u32_e32 v146, s0, v1
	v_add_u32_e32 v174, s1, v1
	ds_read_b128 v[134:137], v146
	ds_read_b128 v[138:141], v146 offset:1024
	ds_read_b128 v[142:145], v146 offset:2048
	ds_read_b128 v[146:149], v146 offset:3072
	ds_read_b128 v[150:153], v174
	ds_read_b128 v[154:157], v174 offset:1024
	ds_read_b128 v[158:161], v174 offset:2048
	ds_read_b128 v[174:177], v174 offset:3072
	v_lshl_add_u64 v[220:221], s[76:77], 0, v[170:171]
	s_add_i32 m0, s67, 0xc000
	ds_read_b128 v[178:181], v222
	ds_read_b128 v[182:185], v222 offset:1024
	ds_read_b128 v[186:189], v222 offset:2048
	ds_read_b128 v[190:193], v222 offset:3072
	ds_read_b128 v[204:207], v222 offset:4096
	ds_read_b128 v[208:211], v222 offset:5120
	ds_read_b128 v[212:215], v222 offset:6144
	ds_read_b128 v[216:219], v222 offset:7168
	global_load_lds_dwordx4 v[220:221], off
	v_lshl_add_u64 v[220:221], s[76:77], 0, v[172:173]
	s_add_i32 m0, s67, 0xe000
	s_nop 0
	global_load_lds_dwordx4 v[220:221], off
	s_waitcnt vmcnt(8)
	s_waitcnt lgkmcnt(0)
	s_barrier
	s_setprio 1
	s_waitcnt lgkmcnt(0)
	v_mfma_f32_16x16x32_bf16 v[126:129], v[134:137], v[178:181], v[126:129]
	v_mfma_f32_16x16x32_bf16 v[126:129], v[138:141], v[182:185], v[126:129]
	v_mfma_f32_16x16x32_bf16 v[122:125], v[146:149], v[182:185], v[122:125]
	v_mfma_f32_16x16x32_bf16 v[122:125], v[142:145], v[178:181], v[122:125]
	v_mfma_f32_16x16x32_bf16 v[106:109], v[142:145], v[186:189], v[106:109]
	v_mfma_f32_16x16x32_bf16 v[106:109], v[146:149], v[190:193], v[106:109]
	v_mfma_f32_16x16x32_bf16 v[110:113], v[138:141], v[190:193], v[110:113]
	v_mfma_f32_16x16x32_bf16 v[110:113], v[134:137], v[186:189], v[110:113]
	v_mfma_f32_16x16x32_bf16 v[94:97], v[134:137], v[204:207], v[94:97]
	v_mfma_f32_16x16x32_bf16 v[94:97], v[138:141], v[208:211], v[94:97]
	v_mfma_f32_16x16x32_bf16 v[90:93], v[146:149], v[208:211], v[90:93]
	v_mfma_f32_16x16x32_bf16 v[90:93], v[142:145], v[204:207], v[90:93]
	v_mfma_f32_16x16x32_bf16 v[74:77], v[142:145], v[212:215], v[74:77]
	v_mfma_f32_16x16x32_bf16 v[74:77], v[146:149], v[216:219], v[74:77]
	v_mfma_f32_16x16x32_bf16 v[78:81], v[138:141], v[216:219], v[78:81]
	v_mfma_f32_16x16x32_bf16 v[78:81], v[134:137], v[212:215], v[78:81]
	s_setprio 0
	s_setprio 1
	v_mfma_f32_16x16x32_bf16 v[118:121], v[150:153], v[178:181], v[118:121]
	v_mfma_f32_16x16x32_bf16 v[118:121], v[154:157], v[182:185], v[118:121]
	v_mfma_f32_16x16x32_bf16 v[114:117], v[174:177], v[182:185], v[114:117]
	v_mfma_f32_16x16x32_bf16 v[114:117], v[158:161], v[178:181], v[114:117]
	v_mfma_f32_16x16x32_bf16 v[98:101], v[158:161], v[186:189], v[98:101]
	v_mfma_f32_16x16x32_bf16 v[98:101], v[174:177], v[190:193], v[98:101]
	v_mfma_f32_16x16x32_bf16 v[102:105], v[154:157], v[190:193], v[102:105]
	v_mfma_f32_16x16x32_bf16 v[102:105], v[150:153], v[186:189], v[102:105]
	v_mfma_f32_16x16x32_bf16 v[86:89], v[150:153], v[204:207], v[86:89]
	v_mfma_f32_16x16x32_bf16 v[86:89], v[154:157], v[208:211], v[86:89]
	v_mfma_f32_16x16x32_bf16 v[82:85], v[174:177], v[208:211], v[82:85]
	v_mfma_f32_16x16x32_bf16 v[82:85], v[158:161], v[204:207], v[82:85]
	v_mfma_f32_16x16x32_bf16 v[66:69], v[158:161], v[212:215], v[66:69]
	v_mfma_f32_16x16x32_bf16 v[66:69], v[174:177], v[216:219], v[66:69]
	v_mfma_f32_16x16x32_bf16 v[70:73], v[154:157], v[216:219], v[70:73]
	v_mfma_f32_16x16x32_bf16 v[70:73], v[150:153], v[212:215], v[70:73]
	s_setprio 0
	s_barrier
	s_add_i32 s0, s0, s54
	v_lshl_add_u64 v[220:221], s[70:71], 0, v[164:165]
	s_mov_b32 m0, s0
	ds_read_b128 v[178:181], v222 offset:16384
	ds_read_b128 v[182:185], v222 offset:17408
	ds_read_b128 v[186:189], v222 offset:18432
	ds_read_b128 v[190:193], v222 offset:19456
	ds_read_b128 v[204:207], v222 offset:20480
	ds_read_b128 v[208:211], v222 offset:21504
	ds_read_b128 v[212:215], v222 offset:22528
	ds_read_b128 v[216:219], v222 offset:23552
	global_load_lds_dwordx4 v[220:221], off
	s_add_i32 m0, s0, 0x2000
	s_add_u32 s44, s70, 0x80000
	v_lshl_add_u64 v[224:225], s[70:71], 0, v[162:163]
	s_addc_u32 s45, s71, 0
	s_add_i32 s0, s1, s54
	global_load_lds_dwordx4 v[224:225], off
	v_lshl_add_u64 v[226:227], s[44:45], 0, v[164:165]
	s_mov_b32 m0, s0
	v_lshl_add_u64 v[228:229], vcc, 0, v[162:163]
	global_load_lds_dwordx4 v[226:227], off
	v_lshl_add_u64 v[226:227], s[44:45], 0, v[162:163]
	s_add_i32 m0, s0, 0x2000
	s_nop 0
	global_load_lds_dwordx4 v[226:227], off
	v_lshl_add_u64 v[226:227], vcc, 0, v[164:165]
	s_mov_b32 m0, s67
	s_nop 0
	global_load_lds_dwordx4 v[226:227], off
	s_mov_b32 m0, s68
	s_nop 0
	global_load_lds_dwordx4 v[228:229], off
	s_waitcnt vmcnt(8)
	s_waitcnt lgkmcnt(0)
	s_barrier
	s_setprio 1
	s_waitcnt lgkmcnt(0)
	v_mfma_f32_16x16x32_bf16 v[62:65], v[134:137], v[178:181], v[62:65]
	v_mfma_f32_16x16x32_bf16 v[62:65], v[138:141], v[182:185], v[62:65]
	v_mfma_f32_16x16x32_bf16 v[58:61], v[146:149], v[182:185], v[58:61]
	v_mfma_f32_16x16x32_bf16 v[58:61], v[142:145], v[178:181], v[58:61]
	v_mfma_f32_16x16x32_bf16 v[42:45], v[142:145], v[186:189], v[42:45]
	v_mfma_f32_16x16x32_bf16 v[42:45], v[146:149], v[190:193], v[42:45]
	v_mfma_f32_16x16x32_bf16 v[46:49], v[138:141], v[190:193], v[46:49]
	v_mfma_f32_16x16x32_bf16 v[46:49], v[134:137], v[186:189], v[46:49]
	v_mfma_f32_16x16x32_bf16 v[30:33], v[134:137], v[204:207], v[30:33]
	v_mfma_f32_16x16x32_bf16 v[30:33], v[138:141], v[208:211], v[30:33]
	v_mfma_f32_16x16x32_bf16 v[26:29], v[146:149], v[208:211], v[26:29]
	v_mfma_f32_16x16x32_bf16 v[26:29], v[142:145], v[204:207], v[26:29]
	v_mfma_f32_16x16x32_bf16 v[10:13], v[142:145], v[212:215], v[10:13]
	v_mfma_f32_16x16x32_bf16 v[10:13], v[146:149], v[216:219], v[10:13]
	v_mfma_f32_16x16x32_bf16 v[14:17], v[138:141], v[216:219], v[14:17]
	v_mfma_f32_16x16x32_bf16 v[14:17], v[134:137], v[212:215], v[14:17]
	s_setprio 0
	s_setprio 1
	v_mfma_f32_16x16x32_bf16 v[54:57], v[150:153], v[178:181], v[54:57]
	v_mfma_f32_16x16x32_bf16 v[54:57], v[154:157], v[182:185], v[54:57]
	v_mfma_f32_16x16x32_bf16 v[50:53], v[174:177], v[182:185], v[50:53]
	v_mfma_f32_16x16x32_bf16 v[50:53], v[158:161], v[178:181], v[50:53]
	v_mfma_f32_16x16x32_bf16 v[34:37], v[158:161], v[186:189], v[34:37]
	v_mfma_f32_16x16x32_bf16 v[34:37], v[174:177], v[190:193], v[34:37]
	v_mfma_f32_16x16x32_bf16 v[38:41], v[154:157], v[190:193], v[38:41]
	v_mfma_f32_16x16x32_bf16 v[38:41], v[150:153], v[186:189], v[38:41]
	v_mfma_f32_16x16x32_bf16 v[22:25], v[150:153], v[204:207], v[22:25]
	v_mfma_f32_16x16x32_bf16 v[22:25], v[154:157], v[208:211], v[22:25]
	v_mfma_f32_16x16x32_bf16 v[18:21], v[174:177], v[208:211], v[18:21]
	v_mfma_f32_16x16x32_bf16 v[18:21], v[158:161], v[204:207], v[18:21]
	v_mfma_f32_16x16x32_bf16 v[2:5], v[158:161], v[212:215], v[2:5]
	v_mfma_f32_16x16x32_bf16 v[2:5], v[174:177], v[216:219], v[2:5]
	v_mfma_f32_16x16x32_bf16 v[6:9], v[154:157], v[216:219], v[6:9]
	v_mfma_f32_16x16x32_bf16 v[6:9], v[150:153], v[212:215], v[6:9]
	s_setprio 0
	s_barrier
	s_add_i32 s0, 0, 0x18000
	s_add_i32 s1, 0, 0x1c000
	v_add_u32_e32 v146, s0, v1
	v_add_u32_e32 v174, s1, v1
	ds_read_b128 v[134:137], v146
	ds_read_b128 v[138:141], v146 offset:1024
	ds_read_b128 v[142:145], v146 offset:2048
	ds_read_b128 v[146:149], v146 offset:3072
	ds_read_b128 v[150:153], v174
	ds_read_b128 v[154:157], v174 offset:1024
	ds_read_b128 v[158:161], v174 offset:2048
	ds_read_b128 v[174:177], v174 offset:3072
	s_add_u32 s44, vcc_lo, 0x80000
	s_addc_u32 s45, vcc_hi, 0
	s_mov_b32 m0, s8
	v_lshl_add_u64 v[230:231], s[44:45], 0, v[164:165]
	ds_read_b128 v[178:181], v222 offset:32768
	ds_read_b128 v[182:185], v222 offset:33792
	ds_read_b128 v[186:189], v222 offset:34816
	ds_read_b128 v[190:193], v222 offset:35840
	ds_read_b128 v[204:207], v222 offset:36864
	ds_read_b128 v[208:211], v222 offset:37888
	ds_read_b128 v[212:215], v222 offset:38912
	ds_read_b128 v[216:219], v222 offset:39936
	global_load_lds_dwordx4 v[230:231], off
	v_lshl_add_u64 v[230:231], s[44:45], 0, v[162:163]
	s_mov_b32 m0, s9
	s_nop 0
	global_load_lds_dwordx4 v[230:231], off
	s_waitcnt vmcnt(8)
	s_waitcnt lgkmcnt(0)
	s_barrier
	s_setprio 1
	s_waitcnt lgkmcnt(0)
	v_mfma_f32_16x16x32_bf16 v[126:129], v[134:137], v[178:181], v[126:129]
	v_mfma_f32_16x16x32_bf16 v[126:129], v[138:141], v[182:185], v[126:129]
	v_mfma_f32_16x16x32_bf16 v[122:125], v[146:149], v[182:185], v[122:125]
	v_mfma_f32_16x16x32_bf16 v[122:125], v[142:145], v[178:181], v[122:125]
	v_mfma_f32_16x16x32_bf16 v[106:109], v[142:145], v[186:189], v[106:109]
	v_mfma_f32_16x16x32_bf16 v[106:109], v[146:149], v[190:193], v[106:109]
	v_mfma_f32_16x16x32_bf16 v[110:113], v[138:141], v[190:193], v[110:113]
	v_mfma_f32_16x16x32_bf16 v[110:113], v[134:137], v[186:189], v[110:113]
	v_mfma_f32_16x16x32_bf16 v[94:97], v[134:137], v[204:207], v[94:97]
	v_mfma_f32_16x16x32_bf16 v[94:97], v[138:141], v[208:211], v[94:97]
	v_mfma_f32_16x16x32_bf16 v[90:93], v[146:149], v[208:211], v[90:93]
	v_mfma_f32_16x16x32_bf16 v[90:93], v[142:145], v[204:207], v[90:93]
	v_mfma_f32_16x16x32_bf16 v[74:77], v[142:145], v[212:215], v[74:77]
	v_mfma_f32_16x16x32_bf16 v[74:77], v[146:149], v[216:219], v[74:77]
	v_mfma_f32_16x16x32_bf16 v[78:81], v[138:141], v[216:219], v[78:81]
	v_mfma_f32_16x16x32_bf16 v[78:81], v[134:137], v[212:215], v[78:81]
	s_setprio 0
	s_setprio 1
	v_mfma_f32_16x16x32_bf16 v[118:121], v[150:153], v[178:181], v[118:121]
	v_mfma_f32_16x16x32_bf16 v[118:121], v[154:157], v[182:185], v[118:121]
	v_mfma_f32_16x16x32_bf16 v[114:117], v[174:177], v[182:185], v[114:117]
	v_mfma_f32_16x16x32_bf16 v[114:117], v[158:161], v[178:181], v[114:117]
	v_mfma_f32_16x16x32_bf16 v[98:101], v[158:161], v[186:189], v[98:101]
	v_mfma_f32_16x16x32_bf16 v[98:101], v[174:177], v[190:193], v[98:101]
	v_mfma_f32_16x16x32_bf16 v[102:105], v[154:157], v[190:193], v[102:105]
	v_mfma_f32_16x16x32_bf16 v[102:105], v[150:153], v[186:189], v[102:105]
	v_mfma_f32_16x16x32_bf16 v[86:89], v[150:153], v[204:207], v[86:89]
	v_mfma_f32_16x16x32_bf16 v[86:89], v[154:157], v[208:211], v[86:89]
	v_mfma_f32_16x16x32_bf16 v[82:85], v[174:177], v[208:211], v[82:85]
	v_mfma_f32_16x16x32_bf16 v[82:85], v[158:161], v[204:207], v[82:85]
	v_mfma_f32_16x16x32_bf16 v[66:69], v[158:161], v[212:215], v[66:69]
	v_mfma_f32_16x16x32_bf16 v[66:69], v[174:177], v[216:219], v[66:69]
	v_mfma_f32_16x16x32_bf16 v[70:73], v[154:157], v[216:219], v[70:73]
	v_mfma_f32_16x16x32_bf16 v[70:73], v[150:153], v[212:215], v[70:73]
	s_setprio 0
	s_barrier
	s_add_i32 s0, s0, s54
	v_lshl_add_u64 v[220:221], v[220:221], 0, s[82:83]
	s_mov_b32 m0, s0
	ds_read_b128 v[178:181], v222 offset:49152
	ds_read_b128 v[182:185], v222 offset:50176
	ds_read_b128 v[186:189], v222 offset:51200
	ds_read_b128 v[190:193], v222 offset:52224
	ds_read_b128 v[204:207], v222 offset:53248
	ds_read_b128 v[208:211], v222 offset:54272
	ds_read_b128 v[212:215], v222 offset:55296
	ds_read_b128 v[216:219], v222 offset:56320
	global_load_lds_dwordx4 v[220:221], off
	s_add_i32 m0, s0, 0x2000
	s_add_u32 s44, s70, 0x80080
	v_lshl_add_u64 v[220:221], v[224:225], 0, s[82:83]
	s_addc_u32 s45, s71, 0
	s_add_i32 s0, s1, s54
	global_load_lds_dwordx4 v[220:221], off
	v_lshl_add_u64 v[220:221], s[44:45], 0, v[164:165]
	s_mov_b32 m0, s0
	s_nop 0
	global_load_lds_dwordx4 v[220:221], off
	v_lshl_add_u64 v[220:221], s[44:45], 0, v[162:163]
	s_add_i32 m0, s0, 0x2000
	s_nop 0
	global_load_lds_dwordx4 v[220:221], off
	v_lshl_add_u64 v[220:221], v[226:227], 0, s[82:83]
	s_mov_b32 m0, s27
	s_nop 0
	global_load_lds_dwordx4 v[220:221], off
	v_lshl_add_u64 v[220:221], v[228:229], 0, s[82:83]
	s_mov_b32 m0, s26
	s_nop 0
	global_load_lds_dwordx4 v[220:221], off
	s_waitcnt vmcnt(8)
	s_waitcnt lgkmcnt(0)
	s_barrier
	s_setprio 1
	s_waitcnt lgkmcnt(0)
	v_mfma_f32_16x16x32_bf16 v[62:65], v[134:137], v[178:181], v[62:65]
	v_mfma_f32_16x16x32_bf16 v[62:65], v[138:141], v[182:185], v[62:65]
	v_mfma_f32_16x16x32_bf16 v[58:61], v[146:149], v[182:185], v[58:61]
	v_mfma_f32_16x16x32_bf16 v[58:61], v[142:145], v[178:181], v[58:61]
	v_mfma_f32_16x16x32_bf16 v[42:45], v[142:145], v[186:189], v[42:45]
	v_mfma_f32_16x16x32_bf16 v[42:45], v[146:149], v[190:193], v[42:45]
	v_mfma_f32_16x16x32_bf16 v[46:49], v[138:141], v[190:193], v[46:49]
	v_mfma_f32_16x16x32_bf16 v[46:49], v[134:137], v[186:189], v[46:49]
	v_mfma_f32_16x16x32_bf16 v[30:33], v[134:137], v[204:207], v[30:33]
	v_mfma_f32_16x16x32_bf16 v[30:33], v[138:141], v[208:211], v[30:33]
	v_mfma_f32_16x16x32_bf16 v[26:29], v[146:149], v[208:211], v[26:29]
	v_mfma_f32_16x16x32_bf16 v[26:29], v[142:145], v[204:207], v[26:29]
	v_mfma_f32_16x16x32_bf16 v[10:13], v[142:145], v[212:215], v[10:13]
	v_mfma_f32_16x16x32_bf16 v[10:13], v[146:149], v[216:219], v[10:13]
	v_mfma_f32_16x16x32_bf16 v[14:17], v[138:141], v[216:219], v[14:17]
	v_mfma_f32_16x16x32_bf16 v[14:17], v[134:137], v[212:215], v[14:17]
	s_setprio 0
	s_setprio 1
	v_mfma_f32_16x16x32_bf16 v[54:57], v[150:153], v[178:181], v[54:57]
	v_mfma_f32_16x16x32_bf16 v[54:57], v[154:157], v[182:185], v[54:57]
	v_mfma_f32_16x16x32_bf16 v[50:53], v[174:177], v[182:185], v[50:53]
	v_mfma_f32_16x16x32_bf16 v[50:53], v[158:161], v[178:181], v[50:53]
	v_mfma_f32_16x16x32_bf16 v[34:37], v[158:161], v[186:189], v[34:37]
	v_mfma_f32_16x16x32_bf16 v[34:37], v[174:177], v[190:193], v[34:37]
	v_mfma_f32_16x16x32_bf16 v[38:41], v[154:157], v[190:193], v[38:41]
	v_mfma_f32_16x16x32_bf16 v[38:41], v[150:153], v[186:189], v[38:41]
	v_mfma_f32_16x16x32_bf16 v[22:25], v[150:153], v[204:207], v[22:25]
	v_mfma_f32_16x16x32_bf16 v[22:25], v[154:157], v[208:211], v[22:25]
	v_mfma_f32_16x16x32_bf16 v[18:21], v[174:177], v[208:211], v[18:21]
	v_mfma_f32_16x16x32_bf16 v[18:21], v[158:161], v[204:207], v[18:21]
	v_mfma_f32_16x16x32_bf16 v[2:5], v[158:161], v[212:215], v[2:5]
	v_mfma_f32_16x16x32_bf16 v[2:5], v[174:177], v[216:219], v[2:5]
	v_mfma_f32_16x16x32_bf16 v[6:9], v[154:157], v[216:219], v[6:9]
	v_mfma_f32_16x16x32_bf16 v[6:9], v[150:153], v[212:215], v[6:9]
	s_setprio 0
	s_barrier
	s_add_i32 s43, s43, 2
	s_add_u32 s76, s76, 0x100
	s_addc_u32 s77, s77, 0
	s_add_u32 s7, s7, 0x100
	s_addc_u32 s41, s41, 0
	s_cmp_gt_u32 s43, 29
	s_cbranch_scc1 .LBB0_288

.LBB0_509:
	s_add_u32 s90, s76, 0x100
	s_addc_u32 s91, s77, 0
	s_and_b64 s[0:1], s[70:71], exec
	s_cselect_b32 vcc_hi, s22, s91
	s_cselect_b32 vcc_lo, s23, s90
	s_cselect_b32 s71, s41, s53
	s_cselect_b32 s70, s44, s51
	s_add_i32 s0, 0, 0x10000
	s_add_i32 s18, 0, 0x14000
	v_add_u32_e32 v114, s0, v1
	v_add_u32_e32 v154, s18, v1
	ds_read_b128 v[78:81], v114
	ds_read_b128 v[90:93], v114 offset:1024
	ds_read_b128 v[102:105], v114 offset:2048
	ds_read_b128 v[114:117], v114 offset:3072
	ds_read_b128 v[126:129], v154
	ds_read_b128 v[134:137], v154 offset:1024
	ds_read_b128 v[142:145], v154 offset:2048
	ds_read_b128 v[154:157], v154 offset:3072
	v_lshl_add_u64 v[218:219], s[76:77], 0, v[210:211]
	s_add_i32 m0, s29, 0xc000
	ds_read_b128 v[158:161], v237
	ds_read_b128 v[162:165], v237 offset:1024
	ds_read_b128 v[166:169], v237 offset:2048
	ds_read_b128 v[178:181], v237 offset:3072
	ds_read_b128 v[182:185], v237 offset:4096
	ds_read_b128 v[186:189], v237 offset:5120
	ds_read_b128 v[190:193], v237 offset:6144
	ds_read_b128 v[214:217], v237 offset:7168
	global_load_lds_dwordx4 v[218:219], off
	v_lshl_add_u64 v[218:219], s[76:77], 0, v[212:213]
	s_add_i32 m0, s29, 0xe000
	s_nop 0
	global_load_lds_dwordx4 v[218:219], off
	s_waitcnt vmcnt(8)
	s_waitcnt lgkmcnt(0)
	s_barrier
	s_setprio 1
	s_waitcnt lgkmcnt(0)
	v_mfma_f32_16x16x32_bf16 v[174:177], v[78:81], v[158:161], v[174:177]
	v_mfma_f32_16x16x32_bf16 v[174:177], v[90:93], v[162:165], v[174:177]
	v_mfma_f32_16x16x32_bf16 v[170:173], v[114:117], v[162:165], v[170:173]
	v_mfma_f32_16x16x32_bf16 v[170:173], v[102:105], v[158:161], v[170:173]
	v_mfma_f32_16x16x32_bf16 v[130:133], v[102:105], v[166:169], v[130:133]
	v_mfma_f32_16x16x32_bf16 v[130:133], v[114:117], v[178:181], v[130:133]
	v_mfma_f32_16x16x32_bf16 v[138:141], v[90:93], v[178:181], v[138:141]
	v_mfma_f32_16x16x32_bf16 v[138:141], v[78:81], v[166:169], v[138:141]
	v_mfma_f32_16x16x32_bf16 v[110:113], v[78:81], v[182:185], v[110:113]
	v_mfma_f32_16x16x32_bf16 v[110:113], v[90:93], v[186:189], v[110:113]
	v_mfma_f32_16x16x32_bf16 v[106:109], v[114:117], v[186:189], v[106:109]
	v_mfma_f32_16x16x32_bf16 v[106:109], v[102:105], v[182:185], v[106:109]
	v_mfma_f32_16x16x32_bf16 v[82:85], v[102:105], v[190:193], v[82:85]
	v_mfma_f32_16x16x32_bf16 v[82:85], v[114:117], v[214:217], v[82:85]
	v_mfma_f32_16x16x32_bf16 v[86:89], v[90:93], v[214:217], v[86:89]
	v_mfma_f32_16x16x32_bf16 v[86:89], v[78:81], v[190:193], v[86:89]
	s_setprio 0
	s_setprio 1
	v_mfma_f32_16x16x32_bf16 v[150:153], v[126:129], v[158:161], v[150:153]
	v_mfma_f32_16x16x32_bf16 v[150:153], v[134:137], v[162:165], v[150:153]
	v_mfma_f32_16x16x32_bf16 v[146:149], v[154:157], v[162:165], v[146:149]
	v_mfma_f32_16x16x32_bf16 v[146:149], v[142:145], v[158:161], v[146:149]
	v_mfma_f32_16x16x32_bf16 v[118:121], v[142:145], v[166:169], v[118:121]
	v_mfma_f32_16x16x32_bf16 v[118:121], v[154:157], v[178:181], v[118:121]
	v_mfma_f32_16x16x32_bf16 v[122:125], v[134:137], v[178:181], v[122:125]
	v_mfma_f32_16x16x32_bf16 v[122:125], v[126:129], v[166:169], v[122:125]
	v_mfma_f32_16x16x32_bf16 v[98:101], v[126:129], v[182:185], v[98:101]
	v_mfma_f32_16x16x32_bf16 v[98:101], v[134:137], v[186:189], v[98:101]
	v_mfma_f32_16x16x32_bf16 v[94:97], v[154:157], v[186:189], v[94:97]
	v_mfma_f32_16x16x32_bf16 v[94:97], v[142:145], v[182:185], v[94:97]
	v_mfma_f32_16x16x32_bf16 v[66:69], v[142:145], v[190:193], v[66:69]
	v_mfma_f32_16x16x32_bf16 v[66:69], v[154:157], v[214:217], v[66:69]
	v_mfma_f32_16x16x32_bf16 v[74:77], v[134:137], v[214:217], v[74:77]
	v_mfma_f32_16x16x32_bf16 v[74:77], v[126:129], v[190:193], v[74:77]
	s_setprio 0
	s_barrier
	s_add_i32 s0, s0, s28
	v_lshl_add_u64 v[218:219], s[70:71], 0, v[194:195]
	s_mov_b32 m0, s0
	ds_read_b128 v[158:161], v237 offset:16384
	ds_read_b128 v[162:165], v237 offset:17408
	ds_read_b128 v[166:169], v237 offset:18432
	ds_read_b128 v[178:181], v237 offset:19456
	ds_read_b128 v[182:185], v237 offset:20480
	ds_read_b128 v[186:189], v237 offset:21504
	ds_read_b128 v[190:193], v237 offset:22528
	ds_read_b128 v[214:217], v237 offset:23552
	global_load_lds_dwordx4 v[218:219], off
	s_add_i32 m0, s0, 0x2000
	s_add_u32 s0, s70, 0x80000
	v_lshl_add_u64 v[220:221], s[70:71], 0, v[204:205]
	s_addc_u32 s1, s71, 0
	s_add_i32 s18, s18, s28
	global_load_lds_dwordx4 v[220:221], off
	v_lshl_add_u64 v[222:223], s[0:1], 0, v[194:195]
	s_mov_b32 m0, s18
	v_lshl_add_u64 v[224:225], vcc, 0, v[204:205]
	global_load_lds_dwordx4 v[222:223], off
	v_lshl_add_u64 v[222:223], s[0:1], 0, v[204:205]
	s_add_i32 m0, s18, 0x2000
	s_nop 0
	global_load_lds_dwordx4 v[222:223], off
	v_lshl_add_u64 v[222:223], vcc, 0, v[194:195]
	s_mov_b32 m0, s29
	s_nop 0
	global_load_lds_dwordx4 v[222:223], off
	s_mov_b32 m0, s31
	s_nop 0
	global_load_lds_dwordx4 v[224:225], off
	s_waitcnt vmcnt(8)
	s_waitcnt lgkmcnt(0)
	s_barrier
	s_setprio 1
	s_waitcnt lgkmcnt(0)
	v_mfma_f32_16x16x32_bf16 v[62:65], v[78:81], v[158:161], v[62:65]
	v_mfma_f32_16x16x32_bf16 v[62:65], v[90:93], v[162:165], v[62:65]
	v_mfma_f32_16x16x32_bf16 v[58:61], v[114:117], v[162:165], v[58:61]
	v_mfma_f32_16x16x32_bf16 v[58:61], v[102:105], v[158:161], v[58:61]
	v_mfma_f32_16x16x32_bf16 v[42:45], v[102:105], v[166:169], v[42:45]
	v_mfma_f32_16x16x32_bf16 v[42:45], v[114:117], v[178:181], v[42:45]
	v_mfma_f32_16x16x32_bf16 v[46:49], v[90:93], v[178:181], v[46:49]
	v_mfma_f32_16x16x32_bf16 v[46:49], v[78:81], v[166:169], v[46:49]
	v_mfma_f32_16x16x32_bf16 v[30:33], v[78:81], v[182:185], v[30:33]
	v_mfma_f32_16x16x32_bf16 v[30:33], v[90:93], v[186:189], v[30:33]
	v_mfma_f32_16x16x32_bf16 v[26:29], v[114:117], v[186:189], v[26:29]
	v_mfma_f32_16x16x32_bf16 v[26:29], v[102:105], v[182:185], v[26:29]
	v_mfma_f32_16x16x32_bf16 v[10:13], v[102:105], v[190:193], v[10:13]
	v_mfma_f32_16x16x32_bf16 v[10:13], v[114:117], v[214:217], v[10:13]
	v_mfma_f32_16x16x32_bf16 v[14:17], v[90:93], v[214:217], v[14:17]
	v_mfma_f32_16x16x32_bf16 v[14:17], v[78:81], v[190:193], v[14:17]
	s_setprio 0
	s_setprio 1
	v_mfma_f32_16x16x32_bf16 v[54:57], v[126:129], v[158:161], v[54:57]
	v_mfma_f32_16x16x32_bf16 v[54:57], v[134:137], v[162:165], v[54:57]
	v_mfma_f32_16x16x32_bf16 v[50:53], v[154:157], v[162:165], v[50:53]
	v_mfma_f32_16x16x32_bf16 v[50:53], v[142:145], v[158:161], v[50:53]
	v_mfma_f32_16x16x32_bf16 v[34:37], v[142:145], v[166:169], v[34:37]
	v_mfma_f32_16x16x32_bf16 v[34:37], v[154:157], v[178:181], v[34:37]
	v_mfma_f32_16x16x32_bf16 v[38:41], v[134:137], v[178:181], v[38:41]
	v_mfma_f32_16x16x32_bf16 v[38:41], v[126:129], v[166:169], v[38:41]
	v_mfma_f32_16x16x32_bf16 v[22:25], v[126:129], v[182:185], v[22:25]
	v_mfma_f32_16x16x32_bf16 v[22:25], v[134:137], v[186:189], v[22:25]
	v_mfma_f32_16x16x32_bf16 v[18:21], v[154:157], v[186:189], v[18:21]
	v_mfma_f32_16x16x32_bf16 v[18:21], v[142:145], v[182:185], v[18:21]
	v_mfma_f32_16x16x32_bf16 v[2:5], v[142:145], v[190:193], v[2:5]
	v_mfma_f32_16x16x32_bf16 v[2:5], v[154:157], v[214:217], v[2:5]
	v_mfma_f32_16x16x32_bf16 v[6:9], v[134:137], v[214:217], v[6:9]
	v_mfma_f32_16x16x32_bf16 v[6:9], v[126:129], v[190:193], v[6:9]
	s_setprio 0
	s_barrier
	s_add_i32 s18, 0, 0x18000
	s_add_i32 s19, 0, 0x1c000
	v_add_u32_e32 v114, s18, v1
	v_add_u32_e32 v154, s19, v1
	ds_read_b128 v[78:81], v114
	ds_read_b128 v[90:93], v114 offset:1024
	ds_read_b128 v[102:105], v114 offset:2048
	ds_read_b128 v[114:117], v114 offset:3072
	ds_read_b128 v[126:129], v154
	ds_read_b128 v[134:137], v154 offset:1024
	ds_read_b128 v[142:145], v154 offset:2048
	ds_read_b128 v[154:157], v154 offset:3072
	s_add_u32 s0, vcc_lo, 0x80000
	s_addc_u32 s1, vcc_hi, 0
	s_mov_b32 m0, s33
	v_lshl_add_u64 v[226:227], s[0:1], 0, v[194:195]
	ds_read_b128 v[158:161], v237 offset:32768
	ds_read_b128 v[162:165], v237 offset:33792
	ds_read_b128 v[166:169], v237 offset:34816
	ds_read_b128 v[178:181], v237 offset:35840
	ds_read_b128 v[182:185], v237 offset:36864
	ds_read_b128 v[186:189], v237 offset:37888
	ds_read_b128 v[190:193], v237 offset:38912
	ds_read_b128 v[214:217], v237 offset:39936
	global_load_lds_dwordx4 v[226:227], off
	v_lshl_add_u64 v[226:227], s[0:1], 0, v[204:205]
	s_mov_b32 m0, s43
	s_nop 0
	global_load_lds_dwordx4 v[226:227], off
	s_waitcnt vmcnt(8)
	s_waitcnt lgkmcnt(0)
	s_barrier
	s_setprio 1
	s_waitcnt lgkmcnt(0)
	v_mfma_f32_16x16x32_bf16 v[174:177], v[78:81], v[158:161], v[174:177]
	v_mfma_f32_16x16x32_bf16 v[174:177], v[90:93], v[162:165], v[174:177]
	v_mfma_f32_16x16x32_bf16 v[170:173], v[114:117], v[162:165], v[170:173]
	v_mfma_f32_16x16x32_bf16 v[170:173], v[102:105], v[158:161], v[170:173]
	v_mfma_f32_16x16x32_bf16 v[130:133], v[102:105], v[166:169], v[130:133]
	v_mfma_f32_16x16x32_bf16 v[130:133], v[114:117], v[178:181], v[130:133]
	v_mfma_f32_16x16x32_bf16 v[138:141], v[90:93], v[178:181], v[138:141]
	v_mfma_f32_16x16x32_bf16 v[138:141], v[78:81], v[166:169], v[138:141]
	v_mfma_f32_16x16x32_bf16 v[110:113], v[78:81], v[182:185], v[110:113]
	v_mfma_f32_16x16x32_bf16 v[110:113], v[90:93], v[186:189], v[110:113]
	v_mfma_f32_16x16x32_bf16 v[106:109], v[114:117], v[186:189], v[106:109]
	v_mfma_f32_16x16x32_bf16 v[106:109], v[102:105], v[182:185], v[106:109]
	v_mfma_f32_16x16x32_bf16 v[82:85], v[102:105], v[190:193], v[82:85]
	v_mfma_f32_16x16x32_bf16 v[82:85], v[114:117], v[214:217], v[82:85]
	v_mfma_f32_16x16x32_bf16 v[86:89], v[90:93], v[214:217], v[86:89]
	v_mfma_f32_16x16x32_bf16 v[86:89], v[78:81], v[190:193], v[86:89]
	s_setprio 0
	s_setprio 1
	v_mfma_f32_16x16x32_bf16 v[150:153], v[126:129], v[158:161], v[150:153]
	v_mfma_f32_16x16x32_bf16 v[150:153], v[134:137], v[162:165], v[150:153]
	v_mfma_f32_16x16x32_bf16 v[146:149], v[154:157], v[162:165], v[146:149]
	v_mfma_f32_16x16x32_bf16 v[146:149], v[142:145], v[158:161], v[146:149]
	v_mfma_f32_16x16x32_bf16 v[118:121], v[142:145], v[166:169], v[118:121]
	v_mfma_f32_16x16x32_bf16 v[118:121], v[154:157], v[178:181], v[118:121]
	v_mfma_f32_16x16x32_bf16 v[122:125], v[134:137], v[178:181], v[122:125]
	v_mfma_f32_16x16x32_bf16 v[122:125], v[126:129], v[166:169], v[122:125]
	v_mfma_f32_16x16x32_bf16 v[98:101], v[126:129], v[182:185], v[98:101]
	v_mfma_f32_16x16x32_bf16 v[98:101], v[134:137], v[186:189], v[98:101]
	v_mfma_f32_16x16x32_bf16 v[94:97], v[154:157], v[186:189], v[94:97]
	v_mfma_f32_16x16x32_bf16 v[94:97], v[142:145], v[182:185], v[94:97]
	v_mfma_f32_16x16x32_bf16 v[66:69], v[142:145], v[190:193], v[66:69]
	v_mfma_f32_16x16x32_bf16 v[66:69], v[154:157], v[214:217], v[66:69]
	v_mfma_f32_16x16x32_bf16 v[74:77], v[134:137], v[214:217], v[74:77]
	v_mfma_f32_16x16x32_bf16 v[74:77], v[126:129], v[190:193], v[74:77]
	s_setprio 0
	s_barrier
	s_add_i32 s0, s18, s28
	v_lshl_add_u64 v[218:219], v[218:219], 0, s[82:83]
	s_mov_b32 m0, s0
	ds_read_b128 v[158:161], v237 offset:49152
	ds_read_b128 v[162:165], v237 offset:50176
	ds_read_b128 v[166:169], v237 offset:51200
	ds_read_b128 v[178:181], v237 offset:52224
	ds_read_b128 v[182:185], v237 offset:53248
	ds_read_b128 v[186:189], v237 offset:54272
	ds_read_b128 v[190:193], v237 offset:55296
	ds_read_b128 v[214:217], v237 offset:56320
	global_load_lds_dwordx4 v[218:219], off
	s_add_i32 m0, s0, 0x2000
	s_add_u32 s0, s70, 0x80080
	v_lshl_add_u64 v[218:219], v[220:221], 0, s[82:83]
	s_addc_u32 s1, s71, 0
	s_add_i32 s18, s19, s28
	global_load_lds_dwordx4 v[218:219], off
	v_lshl_add_u64 v[218:219], s[0:1], 0, v[194:195]
	s_mov_b32 m0, s18
	s_nop 0
	global_load_lds_dwordx4 v[218:219], off
	v_lshl_add_u64 v[218:219], s[0:1], 0, v[204:205]
	s_add_i32 m0, s18, 0x2000
	s_nop 0
	global_load_lds_dwordx4 v[218:219], off
	v_lshl_add_u64 v[218:219], v[222:223], 0, s[82:83]
	s_mov_b32 m0, s68
	s_nop 0
	global_load_lds_dwordx4 v[218:219], off
	v_lshl_add_u64 v[218:219], v[224:225], 0, s[82:83]
	s_mov_b32 m0, s79
	s_nop 0
	global_load_lds_dwordx4 v[218:219], off
	s_waitcnt vmcnt(8)
	s_waitcnt lgkmcnt(0)
	s_barrier
	s_setprio 1
	s_waitcnt lgkmcnt(0)
	v_mfma_f32_16x16x32_bf16 v[62:65], v[78:81], v[158:161], v[62:65]
	v_mfma_f32_16x16x32_bf16 v[62:65], v[90:93], v[162:165], v[62:65]
	v_mfma_f32_16x16x32_bf16 v[58:61], v[114:117], v[162:165], v[58:61]
	v_mfma_f32_16x16x32_bf16 v[58:61], v[102:105], v[158:161], v[58:61]
	v_mfma_f32_16x16x32_bf16 v[42:45], v[102:105], v[166:169], v[42:45]
	v_mfma_f32_16x16x32_bf16 v[42:45], v[114:117], v[178:181], v[42:45]
	v_mfma_f32_16x16x32_bf16 v[46:49], v[90:93], v[178:181], v[46:49]
	v_mfma_f32_16x16x32_bf16 v[46:49], v[78:81], v[166:169], v[46:49]
	v_mfma_f32_16x16x32_bf16 v[30:33], v[78:81], v[182:185], v[30:33]
	v_mfma_f32_16x16x32_bf16 v[30:33], v[90:93], v[186:189], v[30:33]
	v_mfma_f32_16x16x32_bf16 v[26:29], v[114:117], v[186:189], v[26:29]
	v_mfma_f32_16x16x32_bf16 v[26:29], v[102:105], v[182:185], v[26:29]
	v_mfma_f32_16x16x32_bf16 v[10:13], v[102:105], v[190:193], v[10:13]
	v_mfma_f32_16x16x32_bf16 v[10:13], v[114:117], v[214:217], v[10:13]
	v_mfma_f32_16x16x32_bf16 v[14:17], v[90:93], v[214:217], v[14:17]
	v_mfma_f32_16x16x32_bf16 v[14:17], v[78:81], v[190:193], v[14:17]
	s_setprio 0
	s_setprio 1
	v_mfma_f32_16x16x32_bf16 v[54:57], v[126:129], v[158:161], v[54:57]
	v_mfma_f32_16x16x32_bf16 v[54:57], v[134:137], v[162:165], v[54:57]
	v_mfma_f32_16x16x32_bf16 v[50:53], v[154:157], v[162:165], v[50:53]
	v_mfma_f32_16x16x32_bf16 v[50:53], v[142:145], v[158:161], v[50:53]
	v_mfma_f32_16x16x32_bf16 v[34:37], v[142:145], v[166:169], v[34:37]
	v_mfma_f32_16x16x32_bf16 v[34:37], v[154:157], v[178:181], v[34:37]
	v_mfma_f32_16x16x32_bf16 v[38:41], v[134:137], v[178:181], v[38:41]
	v_mfma_f32_16x16x32_bf16 v[38:41], v[126:129], v[166:169], v[38:41]
	v_mfma_f32_16x16x32_bf16 v[22:25], v[126:129], v[182:185], v[22:25]
	v_mfma_f32_16x16x32_bf16 v[22:25], v[134:137], v[186:189], v[22:25]
	v_mfma_f32_16x16x32_bf16 v[18:21], v[154:157], v[186:189], v[18:21]
	v_mfma_f32_16x16x32_bf16 v[18:21], v[142:145], v[182:185], v[18:21]
	v_mfma_f32_16x16x32_bf16 v[2:5], v[142:145], v[190:193], v[2:5]
	v_mfma_f32_16x16x32_bf16 v[2:5], v[154:157], v[214:217], v[2:5]
	v_mfma_f32_16x16x32_bf16 v[6:9], v[134:137], v[214:217], v[6:9]
	v_mfma_f32_16x16x32_bf16 v[6:9], v[126:129], v[190:193], v[6:9]
	s_setprio 0
	s_barrier
	s_add_i32 s57, s57, 2
	s_add_u32 s51, s51, 0x100
	s_addc_u32 s53, s53, 0
	s_cmp_gt_u32 s57, 29
	s_mov_b64 s[76:77], s[90:91]
	s_cbranch_scc1 .LBB0_512

.LBB0_581:
	s_add_u32 s18, s62, 0xfff80080
	s_addc_u32 s19, s63, -1
	s_and_b64 s[0:1], s[64:65], exec
	s_cselect_b32 s71, s22, s19
	s_cselect_b32 s70, s23, s18
	s_cselect_b32 s65, s39, s58
	s_cselect_b32 s64, s47, s53
	s_add_i32 s0, 0, 0x10000
	v_add_u32_e32 v153, s0, v1
	s_add_i32 s18, 0, 0x14000
	ds_read_b128 v[144:147], v153
	ds_read_b128 v[148:151], v153 offset:1024
	ds_read_b128 v[154:157], v153 offset:2048
	ds_read_b128 v[158:161], v153 offset:3072
	v_add_u32_e32 v153, s18, v1
	ds_read_b128 v[162:165], v153
	ds_read_b128 v[166:169], v153 offset:1024
	ds_read_b128 v[170:173], v153 offset:2048
	ds_read_b128 v[174:177], v153 offset:3072
	v_lshl_add_u64 v[220:221], s[62:63], 0, v[136:137]
	s_add_i32 m0, s29, 0xc000
	ds_read_b128 v[178:181], v152
	ds_read_b128 v[182:185], v152 offset:1024
	ds_read_b128 v[186:189], v152 offset:2048
	ds_read_b128 v[190:193], v152 offset:3072
	ds_read_b128 v[204:207], v152 offset:4096
	ds_read_b128 v[208:211], v152 offset:5120
	ds_read_b128 v[212:215], v152 offset:6144
	ds_read_b128 v[216:219], v152 offset:7168
	global_load_lds_dwordx4 v[220:221], off
	v_lshl_add_u64 v[220:221], s[62:63], 0, v[138:139]
	s_add_i32 m0, s29, 0xe000
	s_nop 0
	global_load_lds_dwordx4 v[220:221], off
	s_waitcnt vmcnt(8)
	s_waitcnt lgkmcnt(0)
	s_barrier
	s_setprio 1
	s_waitcnt lgkmcnt(0)
	v_mfma_f32_16x16x32_bf16 v[126:129], v[144:147], v[178:181], v[126:129]
	v_mfma_f32_16x16x32_bf16 v[126:129], v[148:151], v[182:185], v[126:129]
	v_mfma_f32_16x16x32_bf16 v[122:125], v[158:161], v[182:185], v[122:125]
	v_mfma_f32_16x16x32_bf16 v[122:125], v[154:157], v[178:181], v[122:125]
	v_mfma_f32_16x16x32_bf16 v[106:109], v[154:157], v[186:189], v[106:109]
	v_mfma_f32_16x16x32_bf16 v[106:109], v[158:161], v[190:193], v[106:109]
	v_mfma_f32_16x16x32_bf16 v[110:113], v[148:151], v[190:193], v[110:113]
	v_mfma_f32_16x16x32_bf16 v[110:113], v[144:147], v[186:189], v[110:113]
	v_mfma_f32_16x16x32_bf16 v[94:97], v[144:147], v[204:207], v[94:97]
	v_mfma_f32_16x16x32_bf16 v[94:97], v[148:151], v[208:211], v[94:97]
	v_mfma_f32_16x16x32_bf16 v[90:93], v[158:161], v[208:211], v[90:93]
	v_mfma_f32_16x16x32_bf16 v[90:93], v[154:157], v[204:207], v[90:93]
	v_mfma_f32_16x16x32_bf16 v[74:77], v[154:157], v[212:215], v[74:77]
	v_mfma_f32_16x16x32_bf16 v[74:77], v[158:161], v[216:219], v[74:77]
	v_mfma_f32_16x16x32_bf16 v[78:81], v[148:151], v[216:219], v[78:81]
	v_mfma_f32_16x16x32_bf16 v[78:81], v[144:147], v[212:215], v[78:81]
	s_setprio 0
	s_setprio 1
	v_mfma_f32_16x16x32_bf16 v[118:121], v[162:165], v[178:181], v[118:121]
	v_mfma_f32_16x16x32_bf16 v[118:121], v[166:169], v[182:185], v[118:121]
	v_mfma_f32_16x16x32_bf16 v[114:117], v[174:177], v[182:185], v[114:117]
	v_mfma_f32_16x16x32_bf16 v[114:117], v[170:173], v[178:181], v[114:117]
	v_mfma_f32_16x16x32_bf16 v[98:101], v[170:173], v[186:189], v[98:101]
	v_mfma_f32_16x16x32_bf16 v[98:101], v[174:177], v[190:193], v[98:101]
	v_mfma_f32_16x16x32_bf16 v[102:105], v[166:169], v[190:193], v[102:105]
	v_mfma_f32_16x16x32_bf16 v[102:105], v[162:165], v[186:189], v[102:105]
	v_mfma_f32_16x16x32_bf16 v[86:89], v[162:165], v[204:207], v[86:89]
	v_mfma_f32_16x16x32_bf16 v[86:89], v[166:169], v[208:211], v[86:89]
	v_mfma_f32_16x16x32_bf16 v[82:85], v[174:177], v[208:211], v[82:85]
	v_mfma_f32_16x16x32_bf16 v[82:85], v[170:173], v[204:207], v[82:85]
	v_mfma_f32_16x16x32_bf16 v[66:69], v[170:173], v[212:215], v[66:69]
	v_mfma_f32_16x16x32_bf16 v[66:69], v[174:177], v[216:219], v[66:69]
	v_mfma_f32_16x16x32_bf16 v[70:73], v[166:169], v[216:219], v[70:73]
	v_mfma_f32_16x16x32_bf16 v[70:73], v[162:165], v[212:215], v[70:73]
	s_setprio 0
	s_barrier
	s_add_i32 s0, s0, s28
	v_lshl_add_u64 v[220:221], s[64:65], 0, v[194:195]
	s_mov_b32 m0, s0
	ds_read_b128 v[178:181], v152 offset:16384
	ds_read_b128 v[182:185], v152 offset:17408
	ds_read_b128 v[186:189], v152 offset:18432
	ds_read_b128 v[190:193], v152 offset:19456
	ds_read_b128 v[204:207], v152 offset:20480
	ds_read_b128 v[208:211], v152 offset:21504
	ds_read_b128 v[212:215], v152 offset:22528
	ds_read_b128 v[216:219], v152 offset:23552
	global_load_lds_dwordx4 v[220:221], off
	s_add_i32 m0, s0, 0x2000
	s_add_u32 s0, s64, 0x80000
	v_lshl_add_u64 v[222:223], s[64:65], 0, v[130:131]
	s_addc_u32 s1, s65, 0
	s_add_i32 s18, s18, s28
	global_load_lds_dwordx4 v[222:223], off
	v_lshl_add_u64 v[224:225], s[0:1], 0, v[194:195]
	s_mov_b32 m0, s18
	v_lshl_add_u64 v[226:227], s[70:71], 0, v[130:131]
	global_load_lds_dwordx4 v[224:225], off
	v_lshl_add_u64 v[224:225], s[0:1], 0, v[130:131]
	s_add_i32 m0, s18, 0x2000
	s_nop 0
	global_load_lds_dwordx4 v[224:225], off
	v_lshl_add_u64 v[224:225], s[70:71], 0, v[194:195]
	s_mov_b32 m0, s29
	s_nop 0
	global_load_lds_dwordx4 v[224:225], off
	s_mov_b32 m0, s31
	s_nop 0
	global_load_lds_dwordx4 v[226:227], off
	s_waitcnt vmcnt(8)
	s_waitcnt lgkmcnt(0)
	s_barrier
	s_setprio 1
	s_waitcnt lgkmcnt(0)
	v_mfma_f32_16x16x32_bf16 v[62:65], v[144:147], v[178:181], v[62:65]
	v_mfma_f32_16x16x32_bf16 v[62:65], v[148:151], v[182:185], v[62:65]
	v_mfma_f32_16x16x32_bf16 v[58:61], v[158:161], v[182:185], v[58:61]
	v_mfma_f32_16x16x32_bf16 v[58:61], v[154:157], v[178:181], v[58:61]
	v_mfma_f32_16x16x32_bf16 v[42:45], v[154:157], v[186:189], v[42:45]
	v_mfma_f32_16x16x32_bf16 v[42:45], v[158:161], v[190:193], v[42:45]
	v_mfma_f32_16x16x32_bf16 v[46:49], v[148:151], v[190:193], v[46:49]
	v_mfma_f32_16x16x32_bf16 v[46:49], v[144:147], v[186:189], v[46:49]
	v_mfma_f32_16x16x32_bf16 v[30:33], v[144:147], v[204:207], v[30:33]
	v_mfma_f32_16x16x32_bf16 v[30:33], v[148:151], v[208:211], v[30:33]
	v_mfma_f32_16x16x32_bf16 v[26:29], v[158:161], v[208:211], v[26:29]
	v_mfma_f32_16x16x32_bf16 v[26:29], v[154:157], v[204:207], v[26:29]
	v_mfma_f32_16x16x32_bf16 v[10:13], v[154:157], v[212:215], v[10:13]
	v_mfma_f32_16x16x32_bf16 v[10:13], v[158:161], v[216:219], v[10:13]
	v_mfma_f32_16x16x32_bf16 v[14:17], v[148:151], v[216:219], v[14:17]
	v_mfma_f32_16x16x32_bf16 v[14:17], v[144:147], v[212:215], v[14:17]
	s_setprio 0
	s_setprio 1
	v_mfma_f32_16x16x32_bf16 v[54:57], v[162:165], v[178:181], v[54:57]
	v_mfma_f32_16x16x32_bf16 v[54:57], v[166:169], v[182:185], v[54:57]
	v_mfma_f32_16x16x32_bf16 v[50:53], v[174:177], v[182:185], v[50:53]
	v_mfma_f32_16x16x32_bf16 v[50:53], v[170:173], v[178:181], v[50:53]
	v_mfma_f32_16x16x32_bf16 v[34:37], v[170:173], v[186:189], v[34:37]
	v_mfma_f32_16x16x32_bf16 v[34:37], v[174:177], v[190:193], v[34:37]
	v_mfma_f32_16x16x32_bf16 v[38:41], v[166:169], v[190:193], v[38:41]
	v_mfma_f32_16x16x32_bf16 v[38:41], v[162:165], v[186:189], v[38:41]
	v_mfma_f32_16x16x32_bf16 v[22:25], v[162:165], v[204:207], v[22:25]
	v_mfma_f32_16x16x32_bf16 v[22:25], v[166:169], v[208:211], v[22:25]
	v_mfma_f32_16x16x32_bf16 v[18:21], v[174:177], v[208:211], v[18:21]
	v_mfma_f32_16x16x32_bf16 v[18:21], v[170:173], v[204:207], v[18:21]
	v_mfma_f32_16x16x32_bf16 v[2:5], v[170:173], v[212:215], v[2:5]
	v_mfma_f32_16x16x32_bf16 v[2:5], v[174:177], v[216:219], v[2:5]
	v_mfma_f32_16x16x32_bf16 v[6:9], v[166:169], v[216:219], v[6:9]
	v_mfma_f32_16x16x32_bf16 v[6:9], v[162:165], v[212:215], v[6:9]
	s_setprio 0
	s_barrier
	s_add_i32 s18, 0, 0x18000
	v_add_u32_e32 v153, s18, v1
	s_add_i32 s19, 0, 0x1c000
	ds_read_b128 v[144:147], v153
	ds_read_b128 v[148:151], v153 offset:1024
	ds_read_b128 v[154:157], v153 offset:2048
	ds_read_b128 v[158:161], v153 offset:3072
	v_add_u32_e32 v153, s19, v1
	ds_read_b128 v[162:165], v153
	ds_read_b128 v[166:169], v153 offset:1024
	ds_read_b128 v[170:173], v153 offset:2048
	ds_read_b128 v[174:177], v153 offset:3072
	s_add_u32 s0, s70, 0x80000
	s_addc_u32 s1, s71, 0
	s_mov_b32 m0, s33
	v_lshl_add_u64 v[228:229], s[0:1], 0, v[194:195]
	ds_read_b128 v[178:181], v152 offset:32768
	ds_read_b128 v[182:185], v152 offset:33792
	ds_read_b128 v[186:189], v152 offset:34816
	ds_read_b128 v[190:193], v152 offset:35840
	ds_read_b128 v[204:207], v152 offset:36864
	ds_read_b128 v[208:211], v152 offset:37888
	ds_read_b128 v[212:215], v152 offset:38912
	ds_read_b128 v[216:219], v152 offset:39936
	global_load_lds_dwordx4 v[228:229], off
	v_lshl_add_u64 v[228:229], s[0:1], 0, v[130:131]
	s_mov_b32 m0, s40
	s_nop 0
	global_load_lds_dwordx4 v[228:229], off
	s_waitcnt vmcnt(8)
	s_waitcnt lgkmcnt(0)
	s_barrier
	s_setprio 1
	s_waitcnt lgkmcnt(0)
	v_mfma_f32_16x16x32_bf16 v[126:129], v[144:147], v[178:181], v[126:129]
	v_mfma_f32_16x16x32_bf16 v[126:129], v[148:151], v[182:185], v[126:129]
	v_mfma_f32_16x16x32_bf16 v[122:125], v[158:161], v[182:185], v[122:125]
	v_mfma_f32_16x16x32_bf16 v[122:125], v[154:157], v[178:181], v[122:125]
	v_mfma_f32_16x16x32_bf16 v[106:109], v[154:157], v[186:189], v[106:109]
	v_mfma_f32_16x16x32_bf16 v[106:109], v[158:161], v[190:193], v[106:109]
	v_mfma_f32_16x16x32_bf16 v[110:113], v[148:151], v[190:193], v[110:113]
	v_mfma_f32_16x16x32_bf16 v[110:113], v[144:147], v[186:189], v[110:113]
	v_mfma_f32_16x16x32_bf16 v[94:97], v[144:147], v[204:207], v[94:97]
	v_mfma_f32_16x16x32_bf16 v[94:97], v[148:151], v[208:211], v[94:97]
	v_mfma_f32_16x16x32_bf16 v[90:93], v[158:161], v[208:211], v[90:93]
	v_mfma_f32_16x16x32_bf16 v[90:93], v[154:157], v[204:207], v[90:93]
	v_mfma_f32_16x16x32_bf16 v[74:77], v[154:157], v[212:215], v[74:77]
	v_mfma_f32_16x16x32_bf16 v[74:77], v[158:161], v[216:219], v[74:77]
	v_mfma_f32_16x16x32_bf16 v[78:81], v[148:151], v[216:219], v[78:81]
	v_mfma_f32_16x16x32_bf16 v[78:81], v[144:147], v[212:215], v[78:81]
	s_setprio 0
	s_setprio 1
	v_mfma_f32_16x16x32_bf16 v[118:121], v[162:165], v[178:181], v[118:121]
	v_mfma_f32_16x16x32_bf16 v[118:121], v[166:169], v[182:185], v[118:121]
	v_mfma_f32_16x16x32_bf16 v[114:117], v[174:177], v[182:185], v[114:117]
	v_mfma_f32_16x16x32_bf16 v[114:117], v[170:173], v[178:181], v[114:117]
	v_mfma_f32_16x16x32_bf16 v[98:101], v[170:173], v[186:189], v[98:101]
	v_mfma_f32_16x16x32_bf16 v[98:101], v[174:177], v[190:193], v[98:101]
	v_mfma_f32_16x16x32_bf16 v[102:105], v[166:169], v[190:193], v[102:105]
	v_mfma_f32_16x16x32_bf16 v[102:105], v[162:165], v[186:189], v[102:105]
	v_mfma_f32_16x16x32_bf16 v[86:89], v[162:165], v[204:207], v[86:89]
	v_mfma_f32_16x16x32_bf16 v[86:89], v[166:169], v[208:211], v[86:89]
	v_mfma_f32_16x16x32_bf16 v[82:85], v[174:177], v[208:211], v[82:85]
	v_mfma_f32_16x16x32_bf16 v[82:85], v[170:173], v[204:207], v[82:85]
	v_mfma_f32_16x16x32_bf16 v[66:69], v[170:173], v[212:215], v[66:69]
	v_mfma_f32_16x16x32_bf16 v[66:69], v[174:177], v[216:219], v[66:69]
	v_mfma_f32_16x16x32_bf16 v[70:73], v[166:169], v[216:219], v[70:73]
	v_mfma_f32_16x16x32_bf16 v[70:73], v[162:165], v[212:215], v[70:73]
	s_setprio 0
	s_barrier
	s_add_i32 s0, s18, s28
	v_lshl_add_u64 v[220:221], v[220:221], 0, s[82:83]
	s_mov_b32 m0, s0
	ds_read_b128 v[178:181], v152 offset:49152
	ds_read_b128 v[182:185], v152 offset:50176
	ds_read_b128 v[186:189], v152 offset:51200
	ds_read_b128 v[190:193], v152 offset:52224
	ds_read_b128 v[204:207], v152 offset:53248
	ds_read_b128 v[208:211], v152 offset:54272
	ds_read_b128 v[212:215], v152 offset:55296
	ds_read_b128 v[216:219], v152 offset:56320
	global_load_lds_dwordx4 v[220:221], off
	s_add_i32 m0, s0, 0x2000
	s_add_u32 s0, s64, 0x80080
	v_lshl_add_u64 v[220:221], v[222:223], 0, s[82:83]
	s_addc_u32 s1, s65, 0
	s_add_i32 s18, s19, s28
	global_load_lds_dwordx4 v[220:221], off
	v_lshl_add_u64 v[220:221], s[0:1], 0, v[194:195]
	s_mov_b32 m0, s18
	s_nop 0
	global_load_lds_dwordx4 v[220:221], off
	v_lshl_add_u64 v[220:221], s[0:1], 0, v[130:131]
	s_add_i32 m0, s18, 0x2000
	s_nop 0
	global_load_lds_dwordx4 v[220:221], off
	v_lshl_add_u64 v[220:221], v[224:225], 0, s[82:83]
	s_mov_b32 m0, s54
	s_nop 0
	global_load_lds_dwordx4 v[220:221], off
	v_lshl_add_u64 v[220:221], v[226:227], 0, s[82:83]
	s_mov_b32 m0, s57
	s_nop 0
	global_load_lds_dwordx4 v[220:221], off
	s_waitcnt vmcnt(8)
	s_waitcnt lgkmcnt(0)
	s_barrier
	s_setprio 1
	s_waitcnt lgkmcnt(0)
	v_mfma_f32_16x16x32_bf16 v[62:65], v[144:147], v[178:181], v[62:65]
	v_mfma_f32_16x16x32_bf16 v[62:65], v[148:151], v[182:185], v[62:65]
	v_mfma_f32_16x16x32_bf16 v[58:61], v[158:161], v[182:185], v[58:61]
	v_mfma_f32_16x16x32_bf16 v[58:61], v[154:157], v[178:181], v[58:61]
	v_mfma_f32_16x16x32_bf16 v[42:45], v[154:157], v[186:189], v[42:45]
	v_mfma_f32_16x16x32_bf16 v[42:45], v[158:161], v[190:193], v[42:45]
	v_mfma_f32_16x16x32_bf16 v[46:49], v[148:151], v[190:193], v[46:49]
	v_mfma_f32_16x16x32_bf16 v[46:49], v[144:147], v[186:189], v[46:49]
	v_mfma_f32_16x16x32_bf16 v[30:33], v[144:147], v[204:207], v[30:33]
	v_mfma_f32_16x16x32_bf16 v[30:33], v[148:151], v[208:211], v[30:33]
	v_mfma_f32_16x16x32_bf16 v[26:29], v[158:161], v[208:211], v[26:29]
	v_mfma_f32_16x16x32_bf16 v[26:29], v[154:157], v[204:207], v[26:29]
	v_mfma_f32_16x16x32_bf16 v[10:13], v[154:157], v[212:215], v[10:13]
	v_mfma_f32_16x16x32_bf16 v[10:13], v[158:161], v[216:219], v[10:13]
	v_mfma_f32_16x16x32_bf16 v[14:17], v[148:151], v[216:219], v[14:17]
	v_mfma_f32_16x16x32_bf16 v[14:17], v[144:147], v[212:215], v[14:17]
	s_setprio 0
	s_setprio 1
	v_mfma_f32_16x16x32_bf16 v[54:57], v[162:165], v[178:181], v[54:57]
	v_mfma_f32_16x16x32_bf16 v[54:57], v[166:169], v[182:185], v[54:57]
	v_mfma_f32_16x16x32_bf16 v[50:53], v[174:177], v[182:185], v[50:53]
	v_mfma_f32_16x16x32_bf16 v[50:53], v[170:173], v[178:181], v[50:53]
	v_mfma_f32_16x16x32_bf16 v[34:37], v[170:173], v[186:189], v[34:37]
	v_mfma_f32_16x16x32_bf16 v[34:37], v[174:177], v[190:193], v[34:37]
	v_mfma_f32_16x16x32_bf16 v[38:41], v[166:169], v[190:193], v[38:41]
	v_mfma_f32_16x16x32_bf16 v[38:41], v[162:165], v[186:189], v[38:41]
	v_mfma_f32_16x16x32_bf16 v[22:25], v[162:165], v[204:207], v[22:25]
	v_mfma_f32_16x16x32_bf16 v[22:25], v[166:169], v[208:211], v[22:25]
	v_mfma_f32_16x16x32_bf16 v[18:21], v[174:177], v[208:211], v[18:21]
	v_mfma_f32_16x16x32_bf16 v[18:21], v[170:173], v[204:207], v[18:21]
	v_mfma_f32_16x16x32_bf16 v[2:5], v[170:173], v[212:215], v[2:5]
	v_mfma_f32_16x16x32_bf16 v[2:5], v[174:177], v[216:219], v[2:5]
	v_mfma_f32_16x16x32_bf16 v[6:9], v[166:169], v[216:219], v[6:9]
	v_mfma_f32_16x16x32_bf16 v[6:9], v[162:165], v[212:215], v[6:9]
	s_setprio 0
	s_barrier
	s_add_i32 s76, s76, 2
	s_add_u32 s62, s62, 0x100
	s_addc_u32 s63, s63, 0
	s_add_u32 s53, s53, 0x100
	s_addc_u32 s58, s58, 0
	s_cmp_gt_u32 s76, 29
	s_cbranch_scc1 .LBB0_584

.LBB0_645:
	s_add_u32 s64, s8, 0x100
	s_addc_u32 s65, s9, 0
	s_and_b64 s[0:1], s[70:71], exec
	s_cselect_b32 s77, s63, s65
	s_cselect_b32 s76, s62, s64
	s_cselect_b32 s71, s85, s23
	s_cselect_b32 s70, s84, s7
	s_add_i32 s0, 0, 0x10000
	s_add_i32 s18, 0, 0x14000
	v_add_u32_e32 v106, s0, v1
	v_add_u32_e32 v154, s18, v1
	ds_read_b128 v[70:73], v106
	ds_read_b128 v[82:85], v106 offset:1024
	ds_read_b128 v[94:97], v106 offset:2048
	ds_read_b128 v[106:109], v106 offset:3072
	ds_read_b128 v[118:121], v154
	ds_read_b128 v[130:133], v154 offset:1024
	ds_read_b128 v[142:145], v154 offset:2048
	ds_read_b128 v[154:157], v154 offset:3072
	v_lshl_add_u64 v[218:219], s[8:9], 0, v[206:207]
	s_add_i32 m0, s29, 0xc000
	ds_read_b128 v[158:161], v237
	ds_read_b128 v[170:173], v237 offset:1024
	ds_read_b128 v[174:177], v237 offset:2048
	ds_read_b128 v[178:181], v237 offset:3072
	ds_read_b128 v[182:185], v237 offset:4096
	ds_read_b128 v[186:189], v237 offset:5120
	ds_read_b128 v[210:213], v237 offset:6144
	ds_read_b128 v[214:217], v237 offset:7168
	global_load_lds_dwordx4 v[218:219], off
	v_lshl_add_u64 v[218:219], s[8:9], 0, v[208:209]
	s_add_i32 m0, s29, 0xe000
	s_nop 0
	global_load_lds_dwordx4 v[218:219], off
	s_waitcnt vmcnt(8)
	s_waitcnt lgkmcnt(0)
	s_barrier
	s_setprio 1
	s_waitcnt lgkmcnt(0)
	v_mfma_f32_16x16x32_bf16 v[166:169], v[70:73], v[158:161], v[166:169]
	v_mfma_f32_16x16x32_bf16 v[166:169], v[82:85], v[170:173], v[166:169]
	v_mfma_f32_16x16x32_bf16 v[162:165], v[106:109], v[170:173], v[162:165]
	v_mfma_f32_16x16x32_bf16 v[162:165], v[94:97], v[158:161], v[162:165]
	v_mfma_f32_16x16x32_bf16 v[134:137], v[94:97], v[174:177], v[134:137]
	v_mfma_f32_16x16x32_bf16 v[134:137], v[106:109], v[178:181], v[134:137]
	v_mfma_f32_16x16x32_bf16 v[138:141], v[82:85], v[178:181], v[138:141]
	v_mfma_f32_16x16x32_bf16 v[138:141], v[70:73], v[174:177], v[138:141]
	v_mfma_f32_16x16x32_bf16 v[114:117], v[70:73], v[182:185], v[114:117]
	v_mfma_f32_16x16x32_bf16 v[114:117], v[82:85], v[186:189], v[114:117]
	v_mfma_f32_16x16x32_bf16 v[110:113], v[106:109], v[186:189], v[110:113]
	v_mfma_f32_16x16x32_bf16 v[110:113], v[94:97], v[182:185], v[110:113]
	v_mfma_f32_16x16x32_bf16 v[86:89], v[94:97], v[210:213], v[86:89]
	v_mfma_f32_16x16x32_bf16 v[86:89], v[106:109], v[214:217], v[86:89]
	v_mfma_f32_16x16x32_bf16 v[90:93], v[82:85], v[214:217], v[90:93]
	v_mfma_f32_16x16x32_bf16 v[90:93], v[70:73], v[210:213], v[90:93]
	s_setprio 0
	s_setprio 1
	v_mfma_f32_16x16x32_bf16 v[150:153], v[118:121], v[158:161], v[150:153]
	v_mfma_f32_16x16x32_bf16 v[150:153], v[130:133], v[170:173], v[150:153]
	v_mfma_f32_16x16x32_bf16 v[146:149], v[154:157], v[170:173], v[146:149]
	v_mfma_f32_16x16x32_bf16 v[146:149], v[142:145], v[158:161], v[146:149]
	v_mfma_f32_16x16x32_bf16 v[122:125], v[142:145], v[174:177], v[122:125]
	v_mfma_f32_16x16x32_bf16 v[122:125], v[154:157], v[178:181], v[122:125]
	v_mfma_f32_16x16x32_bf16 v[126:129], v[130:133], v[178:181], v[126:129]
	v_mfma_f32_16x16x32_bf16 v[126:129], v[118:121], v[174:177], v[126:129]
	v_mfma_f32_16x16x32_bf16 v[102:105], v[118:121], v[182:185], v[102:105]
	v_mfma_f32_16x16x32_bf16 v[102:105], v[130:133], v[186:189], v[102:105]
	v_mfma_f32_16x16x32_bf16 v[98:101], v[154:157], v[186:189], v[98:101]
	v_mfma_f32_16x16x32_bf16 v[98:101], v[142:145], v[182:185], v[98:101]
	v_mfma_f32_16x16x32_bf16 v[74:77], v[142:145], v[210:213], v[74:77]
	v_mfma_f32_16x16x32_bf16 v[74:77], v[154:157], v[214:217], v[74:77]
	v_mfma_f32_16x16x32_bf16 v[78:81], v[130:133], v[214:217], v[78:81]
	v_mfma_f32_16x16x32_bf16 v[78:81], v[118:121], v[210:213], v[78:81]
	s_setprio 0
	s_barrier
	s_add_i32 s0, s0, s28
	v_lshl_add_u64 v[218:219], s[70:71], 0, v[192:193]
	s_mov_b32 m0, s0
	ds_read_b128 v[158:161], v237 offset:16384
	ds_read_b128 v[170:173], v237 offset:17408
	ds_read_b128 v[174:177], v237 offset:18432
	ds_read_b128 v[178:181], v237 offset:19456
	ds_read_b128 v[182:185], v237 offset:20480
	ds_read_b128 v[186:189], v237 offset:21504
	ds_read_b128 v[210:213], v237 offset:22528
	ds_read_b128 v[214:217], v237 offset:23552
	global_load_lds_dwordx4 v[218:219], off
	s_add_i32 m0, s0, 0x2000
	s_add_u32 s0, s70, 0x160000
	v_lshl_add_u64 v[220:221], s[70:71], 0, v[190:191]
	s_addc_u32 s1, s71, 0
	s_add_i32 s8, s18, s28
	global_load_lds_dwordx4 v[220:221], off
	v_lshl_add_u64 v[222:223], s[0:1], 0, v[192:193]
	s_mov_b32 m0, s8
	v_lshl_add_u64 v[224:225], s[76:77], 0, v[190:191]
	global_load_lds_dwordx4 v[222:223], off
	v_lshl_add_u64 v[222:223], s[0:1], 0, v[190:191]
	s_add_i32 m0, s8, 0x2000
	s_nop 0
	global_load_lds_dwordx4 v[222:223], off
	v_lshl_add_u64 v[222:223], s[76:77], 0, v[192:193]
	s_mov_b32 m0, s29
	s_nop 0
	global_load_lds_dwordx4 v[222:223], off
	s_mov_b32 m0, s31
	s_nop 0
	global_load_lds_dwordx4 v[224:225], off
	s_waitcnt vmcnt(8)
	s_waitcnt lgkmcnt(0)
	s_barrier
	s_setprio 1
	s_waitcnt lgkmcnt(0)
	v_mfma_f32_16x16x32_bf16 v[62:65], v[70:73], v[158:161], v[62:65]
	v_mfma_f32_16x16x32_bf16 v[62:65], v[82:85], v[170:173], v[62:65]
	v_mfma_f32_16x16x32_bf16 v[58:61], v[106:109], v[170:173], v[58:61]
	v_mfma_f32_16x16x32_bf16 v[58:61], v[94:97], v[158:161], v[58:61]
	v_mfma_f32_16x16x32_bf16 v[42:45], v[94:97], v[174:177], v[42:45]
	v_mfma_f32_16x16x32_bf16 v[42:45], v[106:109], v[178:181], v[42:45]
	v_mfma_f32_16x16x32_bf16 v[46:49], v[82:85], v[178:181], v[46:49]
	v_mfma_f32_16x16x32_bf16 v[46:49], v[70:73], v[174:177], v[46:49]
	v_mfma_f32_16x16x32_bf16 v[30:33], v[70:73], v[182:185], v[30:33]
	v_mfma_f32_16x16x32_bf16 v[30:33], v[82:85], v[186:189], v[30:33]
	v_mfma_f32_16x16x32_bf16 v[26:29], v[106:109], v[186:189], v[26:29]
	v_mfma_f32_16x16x32_bf16 v[26:29], v[94:97], v[182:185], v[26:29]
	v_mfma_f32_16x16x32_bf16 v[10:13], v[94:97], v[210:213], v[10:13]
	v_mfma_f32_16x16x32_bf16 v[10:13], v[106:109], v[214:217], v[10:13]
	v_mfma_f32_16x16x32_bf16 v[14:17], v[82:85], v[214:217], v[14:17]
	v_mfma_f32_16x16x32_bf16 v[14:17], v[70:73], v[210:213], v[14:17]
	s_setprio 0
	s_setprio 1
	v_mfma_f32_16x16x32_bf16 v[54:57], v[118:121], v[158:161], v[54:57]
	v_mfma_f32_16x16x32_bf16 v[54:57], v[130:133], v[170:173], v[54:57]
	v_mfma_f32_16x16x32_bf16 v[50:53], v[154:157], v[170:173], v[50:53]
	v_mfma_f32_16x16x32_bf16 v[50:53], v[142:145], v[158:161], v[50:53]
	v_mfma_f32_16x16x32_bf16 v[34:37], v[142:145], v[174:177], v[34:37]
	v_mfma_f32_16x16x32_bf16 v[34:37], v[154:157], v[178:181], v[34:37]
	v_mfma_f32_16x16x32_bf16 v[38:41], v[130:133], v[178:181], v[38:41]
	v_mfma_f32_16x16x32_bf16 v[38:41], v[118:121], v[174:177], v[38:41]
	v_mfma_f32_16x16x32_bf16 v[22:25], v[118:121], v[182:185], v[22:25]
	v_mfma_f32_16x16x32_bf16 v[22:25], v[130:133], v[186:189], v[22:25]
	v_mfma_f32_16x16x32_bf16 v[18:21], v[154:157], v[186:189], v[18:21]
	v_mfma_f32_16x16x32_bf16 v[18:21], v[142:145], v[182:185], v[18:21]
	v_mfma_f32_16x16x32_bf16 v[2:5], v[142:145], v[210:213], v[2:5]
	v_mfma_f32_16x16x32_bf16 v[2:5], v[154:157], v[214:217], v[2:5]
	v_mfma_f32_16x16x32_bf16 v[6:9], v[130:133], v[214:217], v[6:9]
	v_mfma_f32_16x16x32_bf16 v[6:9], v[118:121], v[210:213], v[6:9]
	s_setprio 0
	s_barrier
	s_add_i32 s8, 0, 0x18000
	s_add_i32 s9, 0, 0x1c000
	v_add_u32_e32 v106, s8, v1
	v_add_u32_e32 v154, s9, v1
	ds_read_b128 v[70:73], v106
	ds_read_b128 v[82:85], v106 offset:1024
	ds_read_b128 v[94:97], v106 offset:2048
	ds_read_b128 v[106:109], v106 offset:3072
	ds_read_b128 v[118:121], v154
	ds_read_b128 v[130:133], v154 offset:1024
	ds_read_b128 v[142:145], v154 offset:2048
	ds_read_b128 v[154:157], v154 offset:3072
	s_add_u32 s0, s76, 0x160000
	s_addc_u32 s1, s77, 0
	s_mov_b32 m0, s33
	v_lshl_add_u64 v[226:227], s[0:1], 0, v[192:193]
	ds_read_b128 v[158:161], v237 offset:32768
	ds_read_b128 v[170:173], v237 offset:33792
	ds_read_b128 v[174:177], v237 offset:34816
	ds_read_b128 v[178:181], v237 offset:35840
	ds_read_b128 v[182:185], v237 offset:36864
	ds_read_b128 v[186:189], v237 offset:37888
	ds_read_b128 v[210:213], v237 offset:38912
	ds_read_b128 v[214:217], v237 offset:39936
	global_load_lds_dwordx4 v[226:227], off
	v_lshl_add_u64 v[226:227], s[0:1], 0, v[190:191]
	s_mov_b32 m0, s43
	s_nop 0
	global_load_lds_dwordx4 v[226:227], off
	s_waitcnt vmcnt(8)
	s_waitcnt lgkmcnt(0)
	s_barrier
	s_setprio 1
	s_waitcnt lgkmcnt(0)
	v_mfma_f32_16x16x32_bf16 v[166:169], v[70:73], v[158:161], v[166:169]
	v_mfma_f32_16x16x32_bf16 v[166:169], v[82:85], v[170:173], v[166:169]
	v_mfma_f32_16x16x32_bf16 v[162:165], v[106:109], v[170:173], v[162:165]
	v_mfma_f32_16x16x32_bf16 v[162:165], v[94:97], v[158:161], v[162:165]
	v_mfma_f32_16x16x32_bf16 v[134:137], v[94:97], v[174:177], v[134:137]
	v_mfma_f32_16x16x32_bf16 v[134:137], v[106:109], v[178:181], v[134:137]
	v_mfma_f32_16x16x32_bf16 v[138:141], v[82:85], v[178:181], v[138:141]
	v_mfma_f32_16x16x32_bf16 v[138:141], v[70:73], v[174:177], v[138:141]
	v_mfma_f32_16x16x32_bf16 v[114:117], v[70:73], v[182:185], v[114:117]
	v_mfma_f32_16x16x32_bf16 v[114:117], v[82:85], v[186:189], v[114:117]
	v_mfma_f32_16x16x32_bf16 v[110:113], v[106:109], v[186:189], v[110:113]
	v_mfma_f32_16x16x32_bf16 v[110:113], v[94:97], v[182:185], v[110:113]
	v_mfma_f32_16x16x32_bf16 v[86:89], v[94:97], v[210:213], v[86:89]
	v_mfma_f32_16x16x32_bf16 v[86:89], v[106:109], v[214:217], v[86:89]
	v_mfma_f32_16x16x32_bf16 v[90:93], v[82:85], v[214:217], v[90:93]
	v_mfma_f32_16x16x32_bf16 v[90:93], v[70:73], v[210:213], v[90:93]
	s_setprio 0
	s_setprio 1
	v_mfma_f32_16x16x32_bf16 v[150:153], v[118:121], v[158:161], v[150:153]
	v_mfma_f32_16x16x32_bf16 v[150:153], v[130:133], v[170:173], v[150:153]
	v_mfma_f32_16x16x32_bf16 v[146:149], v[154:157], v[170:173], v[146:149]
	v_mfma_f32_16x16x32_bf16 v[146:149], v[142:145], v[158:161], v[146:149]
	v_mfma_f32_16x16x32_bf16 v[122:125], v[142:145], v[174:177], v[122:125]
	v_mfma_f32_16x16x32_bf16 v[122:125], v[154:157], v[178:181], v[122:125]
	v_mfma_f32_16x16x32_bf16 v[126:129], v[130:133], v[178:181], v[126:129]
	v_mfma_f32_16x16x32_bf16 v[126:129], v[118:121], v[174:177], v[126:129]
	v_mfma_f32_16x16x32_bf16 v[102:105], v[118:121], v[182:185], v[102:105]
	v_mfma_f32_16x16x32_bf16 v[102:105], v[130:133], v[186:189], v[102:105]
	v_mfma_f32_16x16x32_bf16 v[98:101], v[154:157], v[186:189], v[98:101]
	v_mfma_f32_16x16x32_bf16 v[98:101], v[142:145], v[182:185], v[98:101]
	v_mfma_f32_16x16x32_bf16 v[74:77], v[142:145], v[210:213], v[74:77]
	v_mfma_f32_16x16x32_bf16 v[74:77], v[154:157], v[214:217], v[74:77]
	v_mfma_f32_16x16x32_bf16 v[78:81], v[130:133], v[214:217], v[78:81]
	v_mfma_f32_16x16x32_bf16 v[78:81], v[118:121], v[210:213], v[78:81]
	s_setprio 0
	s_barrier
	s_add_i32 s0, s8, s28
	v_lshl_add_u64 v[218:219], v[218:219], 0, s[82:83]
	s_mov_b32 m0, s0
	ds_read_b128 v[158:161], v237 offset:49152
	ds_read_b128 v[170:173], v237 offset:50176
	ds_read_b128 v[174:177], v237 offset:51200
	ds_read_b128 v[178:181], v237 offset:52224
	ds_read_b128 v[182:185], v237 offset:53248
	ds_read_b128 v[186:189], v237 offset:54272
	ds_read_b128 v[210:213], v237 offset:55296
	ds_read_b128 v[214:217], v237 offset:56320
	global_load_lds_dwordx4 v[218:219], off
	s_add_i32 m0, s0, 0x2000
	s_add_u32 s0, s70, 0x160080
	v_lshl_add_u64 v[218:219], v[220:221], 0, s[82:83]
	s_addc_u32 s1, s71, 0
	s_add_i32 s8, s9, s28
	global_load_lds_dwordx4 v[218:219], off
	v_lshl_add_u64 v[218:219], s[0:1], 0, v[192:193]
	s_mov_b32 m0, s8
	s_nop 0
	global_load_lds_dwordx4 v[218:219], off
	v_lshl_add_u64 v[218:219], s[0:1], 0, v[190:191]
	s_add_i32 m0, s8, 0x2000
	s_nop 0
	global_load_lds_dwordx4 v[218:219], off
	v_lshl_add_u64 v[218:219], v[222:223], 0, s[82:83]
	s_mov_b32 m0, s68
	s_nop 0
	global_load_lds_dwordx4 v[218:219], off
	v_lshl_add_u64 v[218:219], v[224:225], 0, s[82:83]
	s_mov_b32 m0, s79
	s_nop 0
	global_load_lds_dwordx4 v[218:219], off
	s_waitcnt vmcnt(8)
	s_waitcnt lgkmcnt(0)
	s_barrier
	s_setprio 1
	s_waitcnt lgkmcnt(0)
	v_mfma_f32_16x16x32_bf16 v[62:65], v[70:73], v[158:161], v[62:65]
	v_mfma_f32_16x16x32_bf16 v[62:65], v[82:85], v[170:173], v[62:65]
	v_mfma_f32_16x16x32_bf16 v[58:61], v[106:109], v[170:173], v[58:61]
	v_mfma_f32_16x16x32_bf16 v[58:61], v[94:97], v[158:161], v[58:61]
	v_mfma_f32_16x16x32_bf16 v[42:45], v[94:97], v[174:177], v[42:45]
	v_mfma_f32_16x16x32_bf16 v[42:45], v[106:109], v[178:181], v[42:45]
	v_mfma_f32_16x16x32_bf16 v[46:49], v[82:85], v[178:181], v[46:49]
	v_mfma_f32_16x16x32_bf16 v[46:49], v[70:73], v[174:177], v[46:49]
	v_mfma_f32_16x16x32_bf16 v[30:33], v[70:73], v[182:185], v[30:33]
	v_mfma_f32_16x16x32_bf16 v[30:33], v[82:85], v[186:189], v[30:33]
	v_mfma_f32_16x16x32_bf16 v[26:29], v[106:109], v[186:189], v[26:29]
	v_mfma_f32_16x16x32_bf16 v[26:29], v[94:97], v[182:185], v[26:29]
	v_mfma_f32_16x16x32_bf16 v[10:13], v[94:97], v[210:213], v[10:13]
	v_mfma_f32_16x16x32_bf16 v[10:13], v[106:109], v[214:217], v[10:13]
	v_mfma_f32_16x16x32_bf16 v[14:17], v[82:85], v[214:217], v[14:17]
	v_mfma_f32_16x16x32_bf16 v[14:17], v[70:73], v[210:213], v[14:17]
	s_setprio 0
	s_setprio 1
	v_mfma_f32_16x16x32_bf16 v[54:57], v[118:121], v[158:161], v[54:57]
	v_mfma_f32_16x16x32_bf16 v[54:57], v[130:133], v[170:173], v[54:57]
	v_mfma_f32_16x16x32_bf16 v[50:53], v[154:157], v[170:173], v[50:53]
	v_mfma_f32_16x16x32_bf16 v[50:53], v[142:145], v[158:161], v[50:53]
	v_mfma_f32_16x16x32_bf16 v[34:37], v[142:145], v[174:177], v[34:37]
	v_mfma_f32_16x16x32_bf16 v[34:37], v[154:157], v[178:181], v[34:37]
	v_mfma_f32_16x16x32_bf16 v[38:41], v[130:133], v[178:181], v[38:41]
	v_mfma_f32_16x16x32_bf16 v[38:41], v[118:121], v[174:177], v[38:41]
	v_mfma_f32_16x16x32_bf16 v[22:25], v[118:121], v[182:185], v[22:25]
	v_mfma_f32_16x16x32_bf16 v[22:25], v[130:133], v[186:189], v[22:25]
	v_mfma_f32_16x16x32_bf16 v[18:21], v[154:157], v[186:189], v[18:21]
	v_mfma_f32_16x16x32_bf16 v[18:21], v[142:145], v[182:185], v[18:21]
	v_mfma_f32_16x16x32_bf16 v[2:5], v[142:145], v[210:213], v[2:5]
	v_mfma_f32_16x16x32_bf16 v[2:5], v[154:157], v[214:217], v[2:5]
	v_mfma_f32_16x16x32_bf16 v[6:9], v[130:133], v[214:217], v[6:9]
	v_mfma_f32_16x16x32_bf16 v[6:9], v[118:121], v[210:213], v[6:9]
	s_setprio 0
	s_barrier
	s_add_i32 s41, s41, 2
	s_add_u32 s7, s7, 0x100
	s_addc_u32 s23, s23, 0
	s_cmpk_gt_u32 s41, 0x55
	s_mov_b64 s[8:9], s[64:65]
	s_cbranch_scc1 .LBB0_648
